# GEMM tile setup: the 127 accumulator zeroing moves per tile done as 63 64-bit moves + 1
# speedup vs baseline: 1.0130x; 1.0031x over previous
; #define PG8_WAIT_V(n) asm volatile("s_waitcnt vmcnt(" #n ")" ::: "memory")
;     ...
;         const bool has_next = S.next(ui + 1, nxt);
;         const char* nA = has_next ? (const char*)g.A + (size_t)nxt.pm * tA : cA; const char* nB = has_next ? (const char*)g.Bt + (size_t)nxt.pn * tB : cB;
; #pragma unroll 1
;         for (int t = 0; t < nt; t += 2) {
;             const bool last = (t == nt - 2);
;             const char* a1 = cA + (size_t)(t + 1) * kstep;
;             const char* a2 = last ? nA : cA + (size_t)(t + 2) * kstep; const char* b2 = last ? nB : cB + (size_t)(t + 2) * kstep;
;             const char* a3 = a2 + kstep; const char* b3 = b2 + kstep;
;             if (last && has_next) PG8_A_READY(nxt);
;             PG8_LDB(B0, 0, 0); PG8_SCHED; PG8_LDA(At, 0, 0); PG8_STAGE(PG8_SA(1, 1), a1 + hA, voffA);
;             PG8_WAIT_L(8); PG8_BAR; PG8_WAIT_L(0); PG8_MMA(0, 0, At, B0); PG8_BAR; PG8_SCHED;
;             PG8_LDB(B1, 0, 1); PG8_STAGE(PG8_SB(0, 0), b2, voffB);
;             PG8_BAR; PG8_WAIT_L(0); PG8_MMA(0, 1, At, B1); PG8_BAR;
;             PG8_LDA(At, 0, 1); PG8_STAGE(PG8_SA(0, 0), a2, voffA);
;             PG8_BAR; PG8_WAIT_L(0); PG8_MMA(1, 0, At, B0); PG8_BAR; PG8_SCHED;
;             PG8_STAGE(PG8_SB(0, 1), b2 + hB, voffB);
;             PG8_WAIT_V(6); PG8_BAR; PG8_MMA(1, 1, At, B1); PG8_BAR;
;             PG8_LDB(B0, 1, 0); PG8_SCHED; PG8_LDA(At, 1, 0); PG8_STAGE(PG8_SA(0, 1), a2 + hA, voffA);
;             PG8_WAIT_L(8); PG8_BAR; PG8_WAIT_L(0); PG8_MMA(0, 0, At, B0); PG8_BAR; PG8_SCHED;
;             PG8_LDB(B1, 1, 1); PG8_STAGE(PG8_SB(1, 0), b3, voffB);
;             PG8_BAR; PG8_WAIT_L(0); PG8_MMA(0, 1, At, B1); PG8_BAR;
;             PG8_LDA(At, 1, 1); PG8_STAGE(PG8_SA(1, 0), a3, voffA);
;             PG8_BAR; PG8_WAIT_L(0); PG8_MMA(1, 0, At, B0); PG8_BAR; PG8_SCHED;
;             PG8_STAGE(PG8_SB(1, 1), b3 + hB, voffB);
;             PG8_WAIT_V(6); PG8_BAR; PG8_MMA(1, 1, At, B1); PG8_BAR;
;         }
;         E(acc, cur, wr, wc, fr, fq);
;         if (!has_next) break;
; #pragma unroll
;         for (int a = 0; a < 2; ++a)
; #pragma unroll
;             for (int b = 0; b < 2; ++b)
; #pragma unroll
;                 for (int m = 0; m < 4; ++m)
; #pragma unroll
;                     for (int n = 0; n < 2; ++n) acc[a][b][m][n] = (f32x4){0.f, 0.f, 0.f, 0.f};
;         cur = nxt; cA = nA; cB = nB; ++ui;
.LBB0_124:
	s_ashr_i32 s23, s22, 31
	v_cmp_lt_i64_e32 vcc, s[24:25], v[140:141]
	s_lshl_b64 s[24:25], s[22:23], 19
	s_add_u32 s24, s10, s24
	s_addc_u32 s25, s11, s25
	s_and_b64 s[26:27], vcc, exec
	s_cselect_b32 s7, s25, s35
	s_cselect_b32 s23, s24, s34
	s_ashr_i32 s21, s20, 31
	s_lshl_b64 s[26:27], s[20:21], 19
	s_add_u32 s26, s12, s26
	s_addc_u32 s27, s13, s27
	s_and_b64 s[36:37], vcc, exec
	s_cselect_b32 s21, s27, s31
	s_cselect_b32 s33, s26, s30
	s_add_u32 s42, s30, 0x100
	s_addc_u32 s43, s31, 0
	s_add_u32 s30, s34, 0x40080
	v_mov_b32_e32 v0, 0
	s_addc_u32 s31, s35, 0
	s_mov_b32 s44, -2
	v_mov_b32_e32 v1, v0
	v_mov_b64_e32 v[2:3], 0
	v_mov_b64_e32 v[4:5], 0
	v_mov_b64_e32 v[6:7], 0
	v_mov_b64_e32 v[8:9], 0
	v_mov_b64_e32 v[10:11], 0
	v_mov_b64_e32 v[12:13], 0
	v_mov_b64_e32 v[14:15], 0
	v_mov_b64_e32 v[16:17], 0
	v_mov_b64_e32 v[18:19], 0
	v_mov_b64_e32 v[20:21], 0
	v_mov_b64_e32 v[22:23], 0
	v_mov_b64_e32 v[24:25], 0
	v_mov_b64_e32 v[26:27], 0
	v_mov_b64_e32 v[28:29], 0
	v_mov_b64_e32 v[30:31], 0
	v_mov_b64_e32 v[32:33], 0
	v_mov_b64_e32 v[34:35], 0
	v_mov_b64_e32 v[36:37], 0
	v_mov_b64_e32 v[38:39], 0
	v_mov_b64_e32 v[40:41], 0
	v_mov_b64_e32 v[42:43], 0
	v_mov_b64_e32 v[44:45], 0
	v_mov_b64_e32 v[46:47], 0
	v_mov_b64_e32 v[48:49], 0
	v_mov_b64_e32 v[50:51], 0
	v_mov_b64_e32 v[52:53], 0
	v_mov_b64_e32 v[54:55], 0
	v_mov_b64_e32 v[56:57], 0
	v_mov_b64_e32 v[58:59], 0
	v_mov_b64_e32 v[60:61], 0
	v_mov_b64_e32 v[62:63], 0
	v_mov_b64_e32 v[64:65], 0
	v_mov_b64_e32 v[66:67], 0
	v_mov_b64_e32 v[68:69], 0
	v_mov_b64_e32 v[70:71], 0
	v_mov_b64_e32 v[72:73], 0
	v_mov_b64_e32 v[74:75], 0
	v_mov_b64_e32 v[76:77], 0
	v_mov_b64_e32 v[78:79], 0
	v_mov_b64_e32 v[80:81], 0
	v_mov_b64_e32 v[82:83], 0
	v_mov_b64_e32 v[84:85], 0
	v_mov_b64_e32 v[86:87], 0
	v_mov_b64_e32 v[88:89], 0
	v_mov_b64_e32 v[90:91], 0
	v_mov_b64_e32 v[92:93], 0
	v_mov_b64_e32 v[94:95], 0
	v_mov_b64_e32 v[96:97], 0
	v_mov_b64_e32 v[98:99], 0
	v_mov_b64_e32 v[100:101], 0
	v_mov_b64_e32 v[102:103], 0
	v_mov_b64_e32 v[104:105], 0
	v_mov_b64_e32 v[106:107], 0
	v_mov_b64_e32 v[108:109], 0
	v_mov_b64_e32 v[110:111], 0
	v_mov_b64_e32 v[112:113], 0
	v_mov_b64_e32 v[114:115], 0
	v_mov_b64_e32 v[116:117], 0
	v_mov_b64_e32 v[118:119], 0
	v_mov_b64_e32 v[120:121], 0
	v_mov_b64_e32 v[122:123], 0
	v_mov_b64_e32 v[124:125], 0
	v_mov_b64_e32 v[126:127], 0

; #define PG8_WAIT_V(n) asm volatile("s_waitcnt vmcnt(" #n ")" ::: "memory")
;     ...
;         const bool has_next = S.next(ui + 1, nxt);
;         const char* nA = has_next ? (const char*)g.A + (size_t)nxt.pm * tA : cA; const char* nB = has_next ? (const char*)g.Bt + (size_t)nxt.pn * tB : cB;
; #pragma unroll 1
;         for (int t = 0; t < nt; t += 2) {
;             const bool last = (t == nt - 2);
;             const char* a1 = cA + (size_t)(t + 1) * kstep;
;             const char* a2 = last ? nA : cA + (size_t)(t + 2) * kstep; const char* b2 = last ? nB : cB + (size_t)(t + 2) * kstep;
;             const char* a3 = a2 + kstep; const char* b3 = b2 + kstep;
;             if (last && has_next) PG8_A_READY(nxt);
;             PG8_LDB(B0, 0, 0); PG8_SCHED; PG8_LDA(At, 0, 0); PG8_STAGE(PG8_SA(1, 1), a1 + hA, voffA);
;             PG8_WAIT_L(8); PG8_BAR; PG8_WAIT_L(0); PG8_MMA(0, 0, At, B0); PG8_BAR; PG8_SCHED;
;             PG8_LDB(B1, 0, 1); PG8_STAGE(PG8_SB(0, 0), b2, voffB);
;             PG8_BAR; PG8_WAIT_L(0); PG8_MMA(0, 1, At, B1); PG8_BAR;
;             PG8_LDA(At, 0, 1); PG8_STAGE(PG8_SA(0, 0), a2, voffA);
;             PG8_BAR; PG8_WAIT_L(0); PG8_MMA(1, 0, At, B0); PG8_BAR; PG8_SCHED;
;             PG8_STAGE(PG8_SB(0, 1), b2 + hB, voffB);
;             PG8_WAIT_V(6); PG8_BAR; PG8_MMA(1, 1, At, B1); PG8_BAR;
;             PG8_LDB(B0, 1, 0); PG8_SCHED; PG8_LDA(At, 1, 0); PG8_STAGE(PG8_SA(0, 1), a2 + hA, voffA);
;             PG8_WAIT_L(8); PG8_BAR; PG8_WAIT_L(0); PG8_MMA(0, 0, At, B0); PG8_BAR; PG8_SCHED;
;             PG8_LDB(B1, 1, 1); PG8_STAGE(PG8_SB(1, 0), b3, voffB);
;             PG8_BAR; PG8_WAIT_L(0); PG8_MMA(0, 1, At, B1); PG8_BAR;
;             PG8_LDA(At, 1, 1); PG8_STAGE(PG8_SA(1, 0), a3, voffA);
;             PG8_BAR; PG8_WAIT_L(0); PG8_MMA(1, 0, At, B0); PG8_BAR; PG8_SCHED;
;             PG8_STAGE(PG8_SB(1, 1), b3 + hB, voffB);
;             PG8_WAIT_V(6); PG8_BAR; PG8_MMA(1, 1, At, B1); PG8_BAR;
;         }
;         E(acc, cur, wr, wc, fr, fq);
;         if (!has_next) break;
; #pragma unroll
;         for (int a = 0; a < 2; ++a)
; #pragma unroll
;             for (int b = 0; b < 2; ++b)
; #pragma unroll
;                 for (int m = 0; m < 4; ++m)
; #pragma unroll
;                     for (int n = 0; n < 2; ++n) acc[a][b][m][n] = (f32x4){0.f, 0.f, 0.f, 0.f};
;         cur = nxt; cA = nA; cB = nB; ++ui;
.LBB0_331:
	s_ashr_i32 s29, s28, 31
	v_cmp_lt_i64_e32 vcc, s[30:31], v[138:139]
	s_lshl_b64 s[30:31], s[28:29], 17
	s_lshr_b32 s98, s26, 2
	s_lshl_b32 s98, s98, 8
	s_add_u32 s30, s30, s98
	s_add_u32 s30, s10, s30
	s_addc_u32 s31, s11, s31
	s_and_b64 s[34:35], vcc, exec
	s_cselect_b32 s7, s31, s41
	s_cselect_b32 s29, s30, s40
	s_ashr_i32 s27, s26, 31
	s_lshl_b64 s[34:35], s[26:27], 17
	s_add_u32 s34, s34, s98
	s_add_u32 s34, s12, s34
	s_addc_u32 s35, s13, s35
	s_and_b64 s[42:43], vcc, exec
	v_mov_b32_e32 v0, 0
	s_cselect_b32 s27, s35, s39
	s_cselect_b32 s42, s34, s38
	s_mov_b64 s[60:61], 0
	s_mov_b64 s[56:57], 0
	s_mov_b64 s[58:59], -1
	v_mov_b32_e32 v1, v0
	v_mov_b64_e32 v[2:3], 0
	v_mov_b64_e32 v[4:5], 0
	v_mov_b64_e32 v[6:7], 0
	v_mov_b64_e32 v[8:9], 0
	v_mov_b64_e32 v[10:11], 0
	v_mov_b64_e32 v[12:13], 0
	v_mov_b64_e32 v[14:15], 0
	v_mov_b64_e32 v[16:17], 0
	v_mov_b64_e32 v[18:19], 0
	v_mov_b64_e32 v[20:21], 0
	v_mov_b64_e32 v[22:23], 0
	v_mov_b64_e32 v[24:25], 0
	v_mov_b64_e32 v[26:27], 0
	v_mov_b64_e32 v[28:29], 0
	v_mov_b64_e32 v[30:31], 0
	v_mov_b64_e32 v[32:33], 0
	v_mov_b64_e32 v[34:35], 0
	v_mov_b64_e32 v[36:37], 0
	v_mov_b64_e32 v[38:39], 0
	v_mov_b64_e32 v[40:41], 0
	v_mov_b64_e32 v[42:43], 0
	v_mov_b64_e32 v[44:45], 0
	v_mov_b64_e32 v[46:47], 0
	v_mov_b64_e32 v[48:49], 0
	v_mov_b64_e32 v[50:51], 0
	v_mov_b64_e32 v[52:53], 0
	v_mov_b64_e32 v[54:55], 0
	v_mov_b64_e32 v[56:57], 0
	v_mov_b64_e32 v[58:59], 0
	v_mov_b64_e32 v[60:61], 0
	v_mov_b64_e32 v[62:63], 0
	v_mov_b64_e32 v[64:65], 0
	v_mov_b64_e32 v[66:67], 0
	v_mov_b64_e32 v[68:69], 0
	v_mov_b64_e32 v[70:71], 0
	v_mov_b64_e32 v[72:73], 0
	v_mov_b64_e32 v[74:75], 0
	v_mov_b64_e32 v[76:77], 0
	v_mov_b64_e32 v[78:79], 0
	v_mov_b64_e32 v[80:81], 0
	v_mov_b64_e32 v[82:83], 0
	v_mov_b64_e32 v[84:85], 0
	v_mov_b64_e32 v[86:87], 0
	v_mov_b64_e32 v[88:89], 0
	v_mov_b64_e32 v[90:91], 0
	v_mov_b64_e32 v[92:93], 0
	v_mov_b64_e32 v[94:95], 0
	v_mov_b64_e32 v[96:97], 0
	v_mov_b64_e32 v[98:99], 0
	v_mov_b64_e32 v[100:101], 0
	v_mov_b64_e32 v[102:103], 0
	v_mov_b64_e32 v[104:105], 0
	v_mov_b64_e32 v[106:107], 0
	v_mov_b64_e32 v[108:109], 0
	v_mov_b64_e32 v[110:111], 0
	v_mov_b64_e32 v[112:113], 0
	v_mov_b64_e32 v[114:115], 0
	v_mov_b64_e32 v[116:117], 0
	v_mov_b64_e32 v[118:119], 0
	v_mov_b64_e32 v[120:121], 0
	v_mov_b64_e32 v[122:123], 0
	v_mov_b64_e32 v[124:125], 0
	v_mov_b64_e32 v[126:127], 0

; #define PG8_WAIT_V(n) asm volatile("s_waitcnt vmcnt(" #n ")" ::: "memory")
;     ...
;         const bool has_next = S.next(ui + 1, nxt);
;         const char* nA = has_next ? (const char*)g.A + (size_t)nxt.pm * tA : cA; const char* nB = has_next ? (const char*)g.Bt + (size_t)nxt.pn * tB : cB;
; #pragma unroll 1
;         for (int t = 0; t < nt; t += 2) {
;             const bool last = (t == nt - 2);
;             const char* a1 = cA + (size_t)(t + 1) * kstep;
;             const char* a2 = last ? nA : cA + (size_t)(t + 2) * kstep; const char* b2 = last ? nB : cB + (size_t)(t + 2) * kstep;
;             const char* a3 = a2 + kstep; const char* b3 = b2 + kstep;
;             if (last && has_next) PG8_A_READY(nxt);
;             PG8_LDB(B0, 0, 0); PG8_SCHED; PG8_LDA(At, 0, 0); PG8_STAGE(PG8_SA(1, 1), a1 + hA, voffA);
;             PG8_WAIT_L(8); PG8_BAR; PG8_WAIT_L(0); PG8_MMA(0, 0, At, B0); PG8_BAR; PG8_SCHED;
;             PG8_LDB(B1, 0, 1); PG8_STAGE(PG8_SB(0, 0), b2, voffB);
;             PG8_BAR; PG8_WAIT_L(0); PG8_MMA(0, 1, At, B1); PG8_BAR;
;             PG8_LDA(At, 0, 1); PG8_STAGE(PG8_SA(0, 0), a2, voffA);
;             PG8_BAR; PG8_WAIT_L(0); PG8_MMA(1, 0, At, B0); PG8_BAR; PG8_SCHED;
;             PG8_STAGE(PG8_SB(0, 1), b2 + hB, voffB);
;             PG8_WAIT_V(6); PG8_BAR; PG8_MMA(1, 1, At, B1); PG8_BAR;
;             PG8_LDB(B0, 1, 0); PG8_SCHED; PG8_LDA(At, 1, 0); PG8_STAGE(PG8_SA(0, 1), a2 + hA, voffA);
;             PG8_WAIT_L(8); PG8_BAR; PG8_WAIT_L(0); PG8_MMA(0, 0, At, B0); PG8_BAR; PG8_SCHED;
;             PG8_LDB(B1, 1, 1); PG8_STAGE(PG8_SB(1, 0), b3, voffB);
;             PG8_BAR; PG8_WAIT_L(0); PG8_MMA(0, 1, At, B1); PG8_BAR;
;             PG8_LDA(At, 1, 1); PG8_STAGE(PG8_SA(1, 0), a3, voffA);
;             PG8_BAR; PG8_WAIT_L(0); PG8_MMA(1, 0, At, B0); PG8_BAR; PG8_SCHED;
;             PG8_STAGE(PG8_SB(1, 1), b3 + hB, voffB);
;             PG8_WAIT_V(6); PG8_BAR; PG8_MMA(1, 1, At, B1); PG8_BAR;
;         }
;         E(acc, cur, wr, wc, fr, fq);
;         if (!has_next) break;
; #pragma unroll
;         for (int a = 0; a < 2; ++a)
; #pragma unroll
;             for (int b = 0; b < 2; ++b)
; #pragma unroll
;                 for (int m = 0; m < 4; ++m)
; #pragma unroll
;                     for (int n = 0; n < 2; ++n) acc[a][b][m][n] = (f32x4){0.f, 0.f, 0.f, 0.f};
;         cur = nxt; cA = nA; cB = nB; ++ui;
.LBB0_343:
	s_ashr_i32 s23, s22, 31
	v_cmp_lt_i64_e32 vcc, s[24:25], v[158:159]
	s_lshl_b64 s[24:25], s[22:23], 18
	s_lshl_b32 s98, s20, 9
	s_add_u32 s24, s24, s98
	s_add_u32 s24, s10, s24
	s_addc_u32 s25, s11, s25
	s_and_b64 s[26:27], vcc, exec
	s_cselect_b32 s7, s25, s35
	s_cselect_b32 s23, s24, s34
	s_ashr_i32 s21, s20, 31
	s_lshl_b64 s[26:27], s[20:21], 18
	s_add_u32 s26, s26, s98
	s_add_u32 s26, s12, s26
	s_addc_u32 s27, s13, s27
	s_and_b64 s[36:37], vcc, exec
	s_cselect_b32 s21, s27, s31
	s_cselect_b32 s33, s26, s30
	s_add_u32 s42, s30, 0x100
	s_addc_u32 s43, s31, 0
	s_add_u32 s30, s34, 0x20080
	v_mov_b32_e32 v0, 0
	s_addc_u32 s31, s35, 0
	s_mov_b32 s44, -2
	v_mov_b32_e32 v1, v0
	v_mov_b64_e32 v[2:3], 0
	v_mov_b64_e32 v[4:5], 0
	v_mov_b64_e32 v[6:7], 0
	v_mov_b64_e32 v[8:9], 0
	v_mov_b64_e32 v[10:11], 0
	v_mov_b64_e32 v[12:13], 0
	v_mov_b64_e32 v[14:15], 0
	v_mov_b64_e32 v[16:17], 0
	v_mov_b64_e32 v[18:19], 0
	v_mov_b64_e32 v[20:21], 0
	v_mov_b64_e32 v[22:23], 0
	v_mov_b64_e32 v[24:25], 0
	v_mov_b64_e32 v[26:27], 0
	v_mov_b64_e32 v[28:29], 0
	v_mov_b64_e32 v[30:31], 0
	v_mov_b64_e32 v[32:33], 0
	v_mov_b64_e32 v[34:35], 0
	v_mov_b64_e32 v[36:37], 0
	v_mov_b64_e32 v[38:39], 0
	v_mov_b64_e32 v[40:41], 0
	v_mov_b64_e32 v[42:43], 0
	v_mov_b64_e32 v[44:45], 0
	v_mov_b64_e32 v[46:47], 0
	v_mov_b64_e32 v[48:49], 0
	v_mov_b64_e32 v[50:51], 0
	v_mov_b64_e32 v[52:53], 0
	v_mov_b64_e32 v[54:55], 0
	v_mov_b64_e32 v[56:57], 0
	v_mov_b64_e32 v[58:59], 0
	v_mov_b64_e32 v[60:61], 0
	v_mov_b64_e32 v[62:63], 0
	v_mov_b64_e32 v[64:65], 0
	v_mov_b64_e32 v[66:67], 0
	v_mov_b64_e32 v[68:69], 0
	v_mov_b64_e32 v[70:71], 0
	v_mov_b64_e32 v[72:73], 0
	v_mov_b64_e32 v[74:75], 0
	v_mov_b64_e32 v[76:77], 0
	v_mov_b64_e32 v[78:79], 0
	v_mov_b64_e32 v[80:81], 0
	v_mov_b64_e32 v[82:83], 0
	v_mov_b64_e32 v[84:85], 0
	v_mov_b64_e32 v[86:87], 0
	v_mov_b64_e32 v[88:89], 0
	v_mov_b64_e32 v[90:91], 0
	v_mov_b64_e32 v[92:93], 0
	v_mov_b64_e32 v[94:95], 0
	v_mov_b64_e32 v[96:97], 0
	v_mov_b64_e32 v[98:99], 0
	v_mov_b64_e32 v[100:101], 0
	v_mov_b64_e32 v[102:103], 0
	v_mov_b64_e32 v[104:105], 0
	v_mov_b64_e32 v[106:107], 0
	v_mov_b64_e32 v[108:109], 0
	v_mov_b64_e32 v[110:111], 0
	v_mov_b64_e32 v[112:113], 0
	v_mov_b64_e32 v[114:115], 0
	v_mov_b64_e32 v[116:117], 0
	v_mov_b64_e32 v[118:119], 0
	v_mov_b64_e32 v[120:121], 0
	v_mov_b64_e32 v[122:123], 0
	v_mov_b64_e32 v[124:125], 0
	v_mov_b64_e32 v[126:127], 0

; #define PG8_WAIT_V(n) asm volatile("s_waitcnt vmcnt(" #n ")" ::: "memory")
;     ...
;         const bool has_next = S.next(ui + 1, nxt);
;         const char* nA = has_next ? (const char*)g.A + (size_t)nxt.pm * tA : cA; const char* nB = has_next ? (const char*)g.Bt + (size_t)nxt.pn * tB : cB;
; #pragma unroll 1
;         for (int t = 0; t < nt; t += 2) {
;             const bool last = (t == nt - 2);
;             const char* a1 = cA + (size_t)(t + 1) * kstep;
;             const char* a2 = last ? nA : cA + (size_t)(t + 2) * kstep; const char* b2 = last ? nB : cB + (size_t)(t + 2) * kstep;
;             const char* a3 = a2 + kstep; const char* b3 = b2 + kstep;
;             if (last && has_next) PG8_A_READY(nxt);
;             PG8_LDB(B0, 0, 0); PG8_SCHED; PG8_LDA(At, 0, 0); PG8_STAGE(PG8_SA(1, 1), a1 + hA, voffA);
;             PG8_WAIT_L(8); PG8_BAR; PG8_WAIT_L(0); PG8_MMA(0, 0, At, B0); PG8_BAR; PG8_SCHED;
;             PG8_LDB(B1, 0, 1); PG8_STAGE(PG8_SB(0, 0), b2, voffB);
;             PG8_BAR; PG8_WAIT_L(0); PG8_MMA(0, 1, At, B1); PG8_BAR;
;             PG8_LDA(At, 0, 1); PG8_STAGE(PG8_SA(0, 0), a2, voffA);
;             PG8_BAR; PG8_WAIT_L(0); PG8_MMA(1, 0, At, B0); PG8_BAR; PG8_SCHED;
;             PG8_STAGE(PG8_SB(0, 1), b2 + hB, voffB);
;             PG8_WAIT_V(6); PG8_BAR; PG8_MMA(1, 1, At, B1); PG8_BAR;
;             PG8_LDB(B0, 1, 0); PG8_SCHED; PG8_LDA(At, 1, 0); PG8_STAGE(PG8_SA(0, 1), a2 + hA, voffA);
;             PG8_WAIT_L(8); PG8_BAR; PG8_WAIT_L(0); PG8_MMA(0, 0, At, B0); PG8_BAR; PG8_SCHED;
;             PG8_LDB(B1, 1, 1); PG8_STAGE(PG8_SB(1, 0), b3, voffB);
;             PG8_BAR; PG8_WAIT_L(0); PG8_MMA(0, 1, At, B1); PG8_BAR;
;             PG8_LDA(At, 1, 1); PG8_STAGE(PG8_SA(1, 0), a3, voffA);
;             PG8_BAR; PG8_WAIT_L(0); PG8_MMA(1, 0, At, B0); PG8_BAR; PG8_SCHED;
;             PG8_STAGE(PG8_SB(1, 1), b3 + hB, voffB);
;             PG8_WAIT_V(6); PG8_BAR; PG8_MMA(1, 1, At, B1); PG8_BAR;
;         }
;         E(acc, cur, wr, wc, fr, fq);
;         if (!has_next) break;
; #pragma unroll
;         for (int a = 0; a < 2; ++a)
; #pragma unroll
;             for (int b = 0; b < 2; ++b)
; #pragma unroll
;                 for (int m = 0; m < 4; ++m)
; #pragma unroll
;                     for (int n = 0; n < 2; ++n) acc[a][b][m][n] = (f32x4){0.f, 0.f, 0.f, 0.f};
;         cur = nxt; cA = nA; cB = nB; ++ui;
.LBB0_626:
	s_ashr_i32 s29, s28, 31
	s_lshl_b64 s[8:9], s[28:29], 18
	s_add_u32 s34, s22, s8
	s_addc_u32 s35, s23, s9
	s_and_b64 s[8:9], s[12:13], exec
	s_cselect_b32 s8, s35, s17
	s_cselect_b32 s9, s34, s16
	s_add_u32 s29, s16, 0x100
	v_mov_b32_e32 v0, 0
	s_addc_u32 s33, s17, 0
	s_mov_b32 s42, -2
	v_mov_b32_e32 v1, v0
	v_mov_b64_e32 v[2:3], 0
	v_mov_b64_e32 v[4:5], 0
	v_mov_b64_e32 v[6:7], 0
	v_mov_b64_e32 v[8:9], 0
	v_mov_b64_e32 v[10:11], 0
	v_mov_b64_e32 v[12:13], 0
	v_mov_b64_e32 v[14:15], 0
	v_mov_b64_e32 v[16:17], 0
	v_mov_b64_e32 v[18:19], 0
	v_mov_b64_e32 v[20:21], 0
	v_mov_b64_e32 v[22:23], 0
	v_mov_b64_e32 v[24:25], 0
	v_mov_b64_e32 v[26:27], 0
	v_mov_b64_e32 v[28:29], 0
	v_mov_b64_e32 v[30:31], 0
	v_mov_b64_e32 v[32:33], 0
	v_mov_b64_e32 v[34:35], 0
	v_mov_b64_e32 v[36:37], 0
	v_mov_b64_e32 v[38:39], 0
	v_mov_b64_e32 v[40:41], 0
	v_mov_b64_e32 v[42:43], 0
	v_mov_b64_e32 v[44:45], 0
	v_mov_b64_e32 v[46:47], 0
	v_mov_b64_e32 v[48:49], 0
	v_mov_b64_e32 v[50:51], 0
	v_mov_b64_e32 v[52:53], 0
	v_mov_b64_e32 v[54:55], 0
	v_mov_b64_e32 v[56:57], 0
	v_mov_b64_e32 v[58:59], 0
	v_mov_b64_e32 v[60:61], 0
	v_mov_b64_e32 v[62:63], 0
	v_mov_b64_e32 v[64:65], 0
	v_mov_b64_e32 v[66:67], 0
	v_mov_b64_e32 v[68:69], 0
	v_mov_b64_e32 v[70:71], 0
	v_mov_b64_e32 v[72:73], 0
	v_mov_b64_e32 v[74:75], 0
	v_mov_b64_e32 v[76:77], 0
	v_mov_b64_e32 v[78:79], 0
	v_mov_b64_e32 v[80:81], 0
	v_mov_b64_e32 v[82:83], 0
	v_mov_b64_e32 v[84:85], 0
	v_mov_b64_e32 v[86:87], 0
	v_mov_b64_e32 v[88:89], 0
	v_mov_b64_e32 v[90:91], 0
	v_mov_b64_e32 v[92:93], 0
	v_mov_b64_e32 v[94:95], 0
	v_mov_b64_e32 v[96:97], 0
	v_mov_b64_e32 v[98:99], 0
	v_mov_b64_e32 v[100:101], 0
	v_mov_b64_e32 v[102:103], 0
	v_mov_b64_e32 v[104:105], 0
	v_mov_b64_e32 v[106:107], 0
	v_mov_b64_e32 v[108:109], 0
	v_mov_b64_e32 v[110:111], 0
	v_mov_b64_e32 v[112:113], 0
	v_mov_b64_e32 v[114:115], 0
	v_mov_b64_e32 v[116:117], 0
	v_mov_b64_e32 v[118:119], 0
	v_mov_b64_e32 v[120:121], 0
	v_mov_b64_e32 v[122:123], 0
	v_mov_b64_e32 v[124:125], 0
	v_mov_b64_e32 v[126:127], 0

; #define PG8_WAIT_V(n) asm volatile("s_waitcnt vmcnt(" #n ")" ::: "memory")
;     ...
;         const bool has_next = S.next(ui + 1, nxt);
;         const char* nA = has_next ? (const char*)g.A + (size_t)nxt.pm * tA : cA; const char* nB = has_next ? (const char*)g.Bt + (size_t)nxt.pn * tB : cB;
; #pragma unroll 1
;         for (int t = 0; t < nt; t += 2) {
;             const bool last = (t == nt - 2);
;             const char* a1 = cA + (size_t)(t + 1) * kstep;
;             const char* a2 = last ? nA : cA + (size_t)(t + 2) * kstep; const char* b2 = last ? nB : cB + (size_t)(t + 2) * kstep;
;             const char* a3 = a2 + kstep; const char* b3 = b2 + kstep;
;             if (last && has_next) PG8_A_READY(nxt);
;             PG8_LDB(B0, 0, 0); PG8_SCHED; PG8_LDA(At, 0, 0); PG8_STAGE(PG8_SA(1, 1), a1 + hA, voffA);
;             PG8_WAIT_L(8); PG8_BAR; PG8_WAIT_L(0); PG8_MMA(0, 0, At, B0); PG8_BAR; PG8_SCHED;
;             PG8_LDB(B1, 0, 1); PG8_STAGE(PG8_SB(0, 0), b2, voffB);
;             PG8_BAR; PG8_WAIT_L(0); PG8_MMA(0, 1, At, B1); PG8_BAR;
;             PG8_LDA(At, 0, 1); PG8_STAGE(PG8_SA(0, 0), a2, voffA);
;             PG8_BAR; PG8_WAIT_L(0); PG8_MMA(1, 0, At, B0); PG8_BAR; PG8_SCHED;
;             PG8_STAGE(PG8_SB(0, 1), b2 + hB, voffB);
;             PG8_WAIT_V(6); PG8_BAR; PG8_MMA(1, 1, At, B1); PG8_BAR;
;             PG8_LDB(B0, 1, 0); PG8_SCHED; PG8_LDA(At, 1, 0); PG8_STAGE(PG8_SA(0, 1), a2 + hA, voffA);
;             PG8_WAIT_L(8); PG8_BAR; PG8_WAIT_L(0); PG8_MMA(0, 0, At, B0); PG8_BAR; PG8_SCHED;
;             PG8_LDB(B1, 1, 1); PG8_STAGE(PG8_SB(1, 0), b3, voffB);
;             PG8_BAR; PG8_WAIT_L(0); PG8_MMA(0, 1, At, B1); PG8_BAR;
;             PG8_LDA(At, 1, 1); PG8_STAGE(PG8_SA(1, 0), a3, voffA);
;             PG8_BAR; PG8_WAIT_L(0); PG8_MMA(1, 0, At, B0); PG8_BAR; PG8_SCHED;
;             PG8_STAGE(PG8_SB(1, 1), b3 + hB, voffB);
;             PG8_WAIT_V(6); PG8_BAR; PG8_MMA(1, 1, At, B1); PG8_BAR;
;         }
;         E(acc, cur, wr, wc, fr, fq);
;         if (!has_next) break;
; #pragma unroll
;         for (int a = 0; a < 2; ++a)
; #pragma unroll
;             for (int b = 0; b < 2; ++b)
; #pragma unroll
;                 for (int m = 0; m < 4; ++m)
; #pragma unroll
;                     for (int n = 0; n < 2; ++n) acc[a][b][m][n] = (f32x4){0.f, 0.f, 0.f, 0.f};
;         cur = nxt; cA = nA; cB = nB; ++ui;
.LBB0_699:
	s_ashr_i32 s41, s40, 31
	s_lshl_b64 s[8:9], s[40:41], 18
	s_add_u32 s58, s64, s8
	v_cmp_lt_i64_e32 vcc, s[18:19], v[140:141]
	s_addc_u32 s59, s65, s9
	s_and_b64 s[8:9], vcc, exec
	s_cselect_b32 s7, s59, s15
	s_cselect_b32 s8, s58, s14
	s_ashr_i32 s61, s60, 31
	s_lshl_b64 s[18:19], s[60:61], 18
	s_add_u32 s56, s22, s18
	s_addc_u32 s57, s23, s19
	s_and_b64 s[18:19], vcc, exec
	s_cselect_b32 s9, s57, s17
	s_cselect_b32 s20, s56, s16
	s_add_u32 s21, s16, 0x100
	s_addc_u32 s33, s17, 0
	s_add_u32 s14, s14, 0x20080
	v_mov_b32_e32 v0, 0
	s_addc_u32 s15, s15, 0
	s_mov_b32 s41, -2
	v_mov_b32_e32 v1, v0
	v_mov_b64_e32 v[2:3], 0
	v_mov_b64_e32 v[4:5], 0
	v_mov_b64_e32 v[6:7], 0
	v_mov_b64_e32 v[8:9], 0
	v_mov_b64_e32 v[10:11], 0
	v_mov_b64_e32 v[12:13], 0
	v_mov_b64_e32 v[14:15], 0
	v_mov_b64_e32 v[16:17], 0
	v_mov_b64_e32 v[18:19], 0
	v_mov_b64_e32 v[20:21], 0
	v_mov_b64_e32 v[22:23], 0
	v_mov_b64_e32 v[24:25], 0
	v_mov_b64_e32 v[26:27], 0
	v_mov_b64_e32 v[28:29], 0
	v_mov_b64_e32 v[30:31], 0
	v_mov_b64_e32 v[32:33], 0
	v_mov_b64_e32 v[34:35], 0
	v_mov_b64_e32 v[36:37], 0
	v_mov_b64_e32 v[38:39], 0
	v_mov_b64_e32 v[40:41], 0
	v_mov_b64_e32 v[42:43], 0
	v_mov_b64_e32 v[44:45], 0
	v_mov_b64_e32 v[46:47], 0
	v_mov_b64_e32 v[48:49], 0
	v_mov_b64_e32 v[50:51], 0
	v_mov_b64_e32 v[52:53], 0
	v_mov_b64_e32 v[54:55], 0
	v_mov_b64_e32 v[56:57], 0
	v_mov_b64_e32 v[58:59], 0
	v_mov_b64_e32 v[60:61], 0
	v_mov_b64_e32 v[62:63], 0
	v_mov_b64_e32 v[64:65], 0
	v_mov_b64_e32 v[66:67], 0
	v_mov_b64_e32 v[68:69], 0
	v_mov_b64_e32 v[70:71], 0
	v_mov_b64_e32 v[72:73], 0
	v_mov_b64_e32 v[74:75], 0
	v_mov_b64_e32 v[76:77], 0
	v_mov_b64_e32 v[78:79], 0
	v_mov_b64_e32 v[80:81], 0
	v_mov_b64_e32 v[82:83], 0
	v_mov_b64_e32 v[84:85], 0
	v_mov_b64_e32 v[86:87], 0
	v_mov_b64_e32 v[88:89], 0
	v_mov_b64_e32 v[90:91], 0
	v_mov_b64_e32 v[92:93], 0
	v_mov_b64_e32 v[94:95], 0
	v_mov_b64_e32 v[96:97], 0
	v_mov_b64_e32 v[98:99], 0
	v_mov_b64_e32 v[100:101], 0
	v_mov_b64_e32 v[102:103], 0
	v_mov_b64_e32 v[104:105], 0
	v_mov_b64_e32 v[106:107], 0
	v_mov_b64_e32 v[108:109], 0
	v_mov_b64_e32 v[110:111], 0
	v_mov_b64_e32 v[112:113], 0
	v_mov_b64_e32 v[114:115], 0
	v_mov_b64_e32 v[116:117], 0
	v_mov_b64_e32 v[118:119], 0
	v_mov_b64_e32 v[120:121], 0
	v_mov_b64_e32 v[122:123], 0
	v_mov_b64_e32 v[124:125], 0
	v_mov_b64_e32 v[126:127], 0

; #define PG8_WAIT_V(n) asm volatile("s_waitcnt vmcnt(" #n ")" ::: "memory")
;     ...
;         const bool has_next = S.next(ui + 1, nxt);
;         const char* nA = has_next ? (const char*)g.A + (size_t)nxt.pm * tA : cA; const char* nB = has_next ? (const char*)g.Bt + (size_t)nxt.pn * tB : cB;
; #pragma unroll 1
;         for (int t = 0; t < nt; t += 2) {
;             const bool last = (t == nt - 2);
;             const char* a1 = cA + (size_t)(t + 1) * kstep;
;             const char* a2 = last ? nA : cA + (size_t)(t + 2) * kstep; const char* b2 = last ? nB : cB + (size_t)(t + 2) * kstep;
;             const char* a3 = a2 + kstep; const char* b3 = b2 + kstep;
;             if (last && has_next) PG8_A_READY(nxt);
;             PG8_LDB(B0, 0, 0); PG8_SCHED; PG8_LDA(At, 0, 0); PG8_STAGE(PG8_SA(1, 1), a1 + hA, voffA);
;             PG8_WAIT_L(8); PG8_BAR; PG8_WAIT_L(0); PG8_MMA(0, 0, At, B0); PG8_BAR; PG8_SCHED;
;             PG8_LDB(B1, 0, 1); PG8_STAGE(PG8_SB(0, 0), b2, voffB);
;             PG8_BAR; PG8_WAIT_L(0); PG8_MMA(0, 1, At, B1); PG8_BAR;
;             PG8_LDA(At, 0, 1); PG8_STAGE(PG8_SA(0, 0), a2, voffA);
;             PG8_BAR; PG8_WAIT_L(0); PG8_MMA(1, 0, At, B0); PG8_BAR; PG8_SCHED;
;             PG8_STAGE(PG8_SB(0, 1), b2 + hB, voffB);
;             PG8_WAIT_V(6); PG8_BAR; PG8_MMA(1, 1, At, B1); PG8_BAR;
;             PG8_LDB(B0, 1, 0); PG8_SCHED; PG8_LDA(At, 1, 0); PG8_STAGE(PG8_SA(0, 1), a2 + hA, voffA);
;             PG8_WAIT_L(8); PG8_BAR; PG8_WAIT_L(0); PG8_MMA(0, 0, At, B0); PG8_BAR; PG8_SCHED;
;             PG8_LDB(B1, 1, 1); PG8_STAGE(PG8_SB(1, 0), b3, voffB);
;             PG8_BAR; PG8_WAIT_L(0); PG8_MMA(0, 1, At, B1); PG8_BAR;
;             PG8_LDA(At, 1, 1); PG8_STAGE(PG8_SA(1, 0), a3, voffA);
;             PG8_BAR; PG8_WAIT_L(0); PG8_MMA(1, 0, At, B0); PG8_BAR; PG8_SCHED;
;             PG8_STAGE(PG8_SB(1, 1), b3 + hB, voffB);
;             PG8_WAIT_V(6); PG8_BAR; PG8_MMA(1, 1, At, B1); PG8_BAR;
;         }
;         E(acc, cur, wr, wc, fr, fq);
;         if (!has_next) break;
; #pragma unroll
;         for (int a = 0; a < 2; ++a)
; #pragma unroll
;             for (int b = 0; b < 2; ++b)
; #pragma unroll
;                 for (int m = 0; m < 4; ++m)
; #pragma unroll
;                     for (int n = 0; n < 2; ++n) acc[a][b][m][n] = (f32x4){0.f, 0.f, 0.f, 0.f};
;         cur = nxt; cA = nA; cB = nB; ++ui;
.LBB0_722:
	s_ashr_i32 s39, s38, 31
	s_lshl_b64 s[8:9], s[38:39], 18
	s_add_u32 s56, s64, s8
	v_cmp_lt_i64_e64 s[16:17], s[16:17], 16
	s_addc_u32 s57, s65, s9
	s_and_b64 s[8:9], s[16:17], exec
	s_cselect_b32 s7, s57, s13
	s_cselect_b32 s8, s56, s12
	s_ashr_i32 s59, s58, 31
	s_lshl_b64 s[18:19], s[58:59], 18
	s_add_u32 s54, s24, s18
	s_addc_u32 s55, s25, s19
	s_and_b64 s[16:17], s[16:17], exec
	s_cselect_b32 s9, s55, s15
	s_cselect_b32 s18, s54, s14
	s_add_u32 s19, s14, 0x100
	s_addc_u32 s33, s15, 0
	s_add_u32 s12, s12, 0x20080
	v_mov_b32_e32 v0, 0
	s_addc_u32 s13, s13, 0
	s_mov_b32 s39, -2
	v_mov_b32_e32 v1, v0
	v_mov_b64_e32 v[2:3], 0
	v_mov_b64_e32 v[4:5], 0
	v_mov_b64_e32 v[6:7], 0
	v_mov_b64_e32 v[8:9], 0
	v_mov_b64_e32 v[10:11], 0
	v_mov_b64_e32 v[12:13], 0
	v_mov_b64_e32 v[14:15], 0
	v_mov_b64_e32 v[16:17], 0
	v_mov_b64_e32 v[18:19], 0
	v_mov_b64_e32 v[20:21], 0
	v_mov_b64_e32 v[22:23], 0
	v_mov_b64_e32 v[24:25], 0
	v_mov_b64_e32 v[26:27], 0
	v_mov_b64_e32 v[28:29], 0
	v_mov_b64_e32 v[30:31], 0
	v_mov_b64_e32 v[32:33], 0
	v_mov_b64_e32 v[34:35], 0
	v_mov_b64_e32 v[36:37], 0
	v_mov_b64_e32 v[38:39], 0
	v_mov_b64_e32 v[40:41], 0
	v_mov_b64_e32 v[42:43], 0
	v_mov_b64_e32 v[44:45], 0
	v_mov_b64_e32 v[46:47], 0
	v_mov_b64_e32 v[48:49], 0
	v_mov_b64_e32 v[50:51], 0
	v_mov_b64_e32 v[52:53], 0
	v_mov_b64_e32 v[54:55], 0
	v_mov_b64_e32 v[56:57], 0
	v_mov_b64_e32 v[58:59], 0
	v_mov_b64_e32 v[60:61], 0
	v_mov_b64_e32 v[62:63], 0
	v_mov_b64_e32 v[64:65], 0
	v_mov_b64_e32 v[66:67], 0
	v_mov_b64_e32 v[68:69], 0
	v_mov_b64_e32 v[70:71], 0
	v_mov_b64_e32 v[72:73], 0
	v_mov_b64_e32 v[74:75], 0
	v_mov_b64_e32 v[76:77], 0
	v_mov_b64_e32 v[78:79], 0
	v_mov_b64_e32 v[80:81], 0
	v_mov_b64_e32 v[82:83], 0
	v_mov_b64_e32 v[84:85], 0
	v_mov_b64_e32 v[86:87], 0
	v_mov_b64_e32 v[88:89], 0
	v_mov_b64_e32 v[90:91], 0
	v_mov_b64_e32 v[92:93], 0
	v_mov_b64_e32 v[94:95], 0
	v_mov_b64_e32 v[96:97], 0
	v_mov_b64_e32 v[98:99], 0
	v_mov_b64_e32 v[100:101], 0
	v_mov_b64_e32 v[102:103], 0
	v_mov_b64_e32 v[104:105], 0
	v_mov_b64_e32 v[106:107], 0
	v_mov_b64_e32 v[108:109], 0
	v_mov_b64_e32 v[110:111], 0
	v_mov_b64_e32 v[112:113], 0
	v_mov_b64_e32 v[114:115], 0
	v_mov_b64_e32 v[116:117], 0
	v_mov_b64_e32 v[118:119], 0
	v_mov_b64_e32 v[120:121], 0
	v_mov_b64_e32 v[122:123], 0
	v_mov_b64_e32 v[124:125], 0
	v_mov_b64_e32 v[126:127], 0

; #define PG8_WAIT_V(n) asm volatile("s_waitcnt vmcnt(" #n ")" ::: "memory")
;     ...
;         const bool has_next = S.next(ui + 1, nxt);
;         const char* nA = has_next ? (const char*)g.A + (size_t)nxt.pm * tA : cA; const char* nB = has_next ? (const char*)g.Bt + (size_t)nxt.pn * tB : cB;
; #pragma unroll 1
;         for (int t = 0; t < nt; t += 2) {
;             const bool last = (t == nt - 2);
;             const char* a1 = cA + (size_t)(t + 1) * kstep;
;             const char* a2 = last ? nA : cA + (size_t)(t + 2) * kstep; const char* b2 = last ? nB : cB + (size_t)(t + 2) * kstep;
;             const char* a3 = a2 + kstep; const char* b3 = b2 + kstep;
;             if (last && has_next) PG8_A_READY(nxt);
;             PG8_LDB(B0, 0, 0); PG8_SCHED; PG8_LDA(At, 0, 0); PG8_STAGE(PG8_SA(1, 1), a1 + hA, voffA);
;             PG8_WAIT_L(8); PG8_BAR; PG8_WAIT_L(0); PG8_MMA(0, 0, At, B0); PG8_BAR; PG8_SCHED;
;             PG8_LDB(B1, 0, 1); PG8_STAGE(PG8_SB(0, 0), b2, voffB);
;             PG8_BAR; PG8_WAIT_L(0); PG8_MMA(0, 1, At, B1); PG8_BAR;
;             PG8_LDA(At, 0, 1); PG8_STAGE(PG8_SA(0, 0), a2, voffA);
;             PG8_BAR; PG8_WAIT_L(0); PG8_MMA(1, 0, At, B0); PG8_BAR; PG8_SCHED;
;             PG8_STAGE(PG8_SB(0, 1), b2 + hB, voffB);
;             PG8_WAIT_V(6); PG8_BAR; PG8_MMA(1, 1, At, B1); PG8_BAR;
;             PG8_LDB(B0, 1, 0); PG8_SCHED; PG8_LDA(At, 1, 0); PG8_STAGE(PG8_SA(0, 1), a2 + hA, voffA);
;             PG8_WAIT_L(8); PG8_BAR; PG8_WAIT_L(0); PG8_MMA(0, 0, At, B0); PG8_BAR; PG8_SCHED;
;             PG8_LDB(B1, 1, 1); PG8_STAGE(PG8_SB(1, 0), b3, voffB);
;             PG8_BAR; PG8_WAIT_L(0); PG8_MMA(0, 1, At, B1); PG8_BAR;
;             PG8_LDA(At, 1, 1); PG8_STAGE(PG8_SA(1, 0), a3, voffA);
;             PG8_BAR; PG8_WAIT_L(0); PG8_MMA(1, 0, At, B0); PG8_BAR; PG8_SCHED;
;             PG8_STAGE(PG8_SB(1, 1), b3 + hB, voffB);
;             PG8_WAIT_V(6); PG8_BAR; PG8_MMA(1, 1, At, B1); PG8_BAR;
;         }
;         E(acc, cur, wr, wc, fr, fq);
;         if (!has_next) break;
; #pragma unroll
;         for (int a = 0; a < 2; ++a)
; #pragma unroll
;             for (int b = 0; b < 2; ++b)
; #pragma unroll
;                 for (int m = 0; m < 4; ++m)
; #pragma unroll
;                     for (int n = 0; n < 2; ++n) acc[a][b][m][n] = (f32x4){0.f, 0.f, 0.f, 0.f};
;         cur = nxt; cA = nA; cB = nB; ++ui;
.LBB0_763:
	s_ashr_i32 s35, s34, 31
	s_lshl_b64 s[6:7], s[34:35], 19
	s_add_u32 s54, s20, s6
	s_addc_u32 s55, s21, s7
	s_and_b64 s[6:7], s[16:17], exec
	s_cselect_b32 s6, s55, s61
	s_cselect_b32 s7, s54, s60
	s_add_u32 s8, s58, 0x110000
	v_mov_b32_e32 v0, 0
	s_addc_u32 s9, s59, 0
	s_mov_b32 s33, 0
	s_waitcnt lgkmcnt(0)
	v_mov_b32_e32 v1, v0
	v_mov_b64_e32 v[2:3], 0
	v_mov_b64_e32 v[4:5], 0
	v_mov_b64_e32 v[6:7], 0
	v_mov_b64_e32 v[8:9], 0
	v_mov_b64_e32 v[10:11], 0
	v_mov_b64_e32 v[12:13], 0
	v_mov_b64_e32 v[14:15], 0
	v_mov_b64_e32 v[16:17], 0
	v_mov_b64_e32 v[18:19], 0
	v_mov_b64_e32 v[20:21], 0
	v_mov_b64_e32 v[22:23], 0
	v_mov_b64_e32 v[24:25], 0
	v_mov_b64_e32 v[26:27], 0
	v_mov_b64_e32 v[28:29], 0
	v_mov_b64_e32 v[30:31], 0
	v_mov_b64_e32 v[32:33], 0
	v_mov_b64_e32 v[34:35], 0
	v_mov_b64_e32 v[36:37], 0
	v_mov_b64_e32 v[38:39], 0
	v_mov_b64_e32 v[40:41], 0
	v_mov_b64_e32 v[42:43], 0
	v_mov_b64_e32 v[44:45], 0
	v_mov_b64_e32 v[46:47], 0
	v_mov_b64_e32 v[48:49], 0
	v_mov_b64_e32 v[50:51], 0
	v_mov_b64_e32 v[52:53], 0
	v_mov_b64_e32 v[54:55], 0
	v_mov_b64_e32 v[56:57], 0
	v_mov_b64_e32 v[58:59], 0
	v_mov_b64_e32 v[60:61], 0
	v_mov_b64_e32 v[62:63], 0
	v_mov_b64_e32 v[64:65], 0
	v_mov_b64_e32 v[66:67], 0
	v_mov_b64_e32 v[68:69], 0
	v_mov_b64_e32 v[70:71], 0
	v_mov_b64_e32 v[72:73], 0
	v_mov_b64_e32 v[74:75], 0
	v_mov_b64_e32 v[76:77], 0
	v_mov_b64_e32 v[78:79], 0
	v_mov_b64_e32 v[80:81], 0
	v_mov_b64_e32 v[82:83], 0
	v_mov_b64_e32 v[84:85], 0
	v_mov_b64_e32 v[86:87], 0
	v_mov_b64_e32 v[88:89], 0
	v_mov_b64_e32 v[90:91], 0
	v_mov_b64_e32 v[92:93], 0
	v_mov_b64_e32 v[94:95], 0
	v_mov_b64_e32 v[96:97], 0
	v_mov_b64_e32 v[98:99], 0
	v_mov_b64_e32 v[100:101], 0
	v_mov_b64_e32 v[102:103], 0
	v_mov_b64_e32 v[104:105], 0
	v_mov_b64_e32 v[106:107], 0
	v_mov_b64_e32 v[108:109], 0
	v_mov_b64_e32 v[110:111], 0
	v_mov_b64_e32 v[112:113], 0
	v_mov_b64_e32 v[114:115], 0
	v_mov_b64_e32 v[116:117], 0
	v_mov_b64_e32 v[118:119], 0
	v_mov_b64_e32 v[120:121], 0
	v_mov_b64_e32 v[122:123], 0
	v_mov_b64_e32 v[124:125], 0
	v_mov_b64_e32 v[126:127], 0
	s_branch .LBB0_767

; #define PG8_WAIT_V(n) asm volatile("s_waitcnt vmcnt(" #n ")" ::: "memory")
;     ...
;         const bool has_next = S.next(ui + 1, nxt);
;         const char* nA = has_next ? (const char*)g.A + (size_t)nxt.pm * tA : cA; const char* nB = has_next ? (const char*)g.Bt + (size_t)nxt.pn * tB : cB;
; #pragma unroll 1
;         for (int t = 0; t < nt; t += 2) {
;             const bool last = (t == nt - 2);
;             const char* a1 = cA + (size_t)(t + 1) * kstep;
;             const char* a2 = last ? nA : cA + (size_t)(t + 2) * kstep; const char* b2 = last ? nB : cB + (size_t)(t + 2) * kstep;
;             const char* a3 = a2 + kstep; const char* b3 = b2 + kstep;
;             if (last && has_next) PG8_A_READY(nxt);
;             PG8_LDB(B0, 0, 0); PG8_SCHED; PG8_LDA(At, 0, 0); PG8_STAGE(PG8_SA(1, 1), a1 + hA, voffA);
;             PG8_WAIT_L(8); PG8_BAR; PG8_WAIT_L(0); PG8_MMA(0, 0, At, B0); PG8_BAR; PG8_SCHED;
;             PG8_LDB(B1, 0, 1); PG8_STAGE(PG8_SB(0, 0), b2, voffB);
;             PG8_BAR; PG8_WAIT_L(0); PG8_MMA(0, 1, At, B1); PG8_BAR;
;             PG8_LDA(At, 0, 1); PG8_STAGE(PG8_SA(0, 0), a2, voffA);
;             PG8_BAR; PG8_WAIT_L(0); PG8_MMA(1, 0, At, B0); PG8_BAR; PG8_SCHED;
;             PG8_STAGE(PG8_SB(0, 1), b2 + hB, voffB);
;             PG8_WAIT_V(6); PG8_BAR; PG8_MMA(1, 1, At, B1); PG8_BAR;
;             PG8_LDB(B0, 1, 0); PG8_SCHED; PG8_LDA(At, 1, 0); PG8_STAGE(PG8_SA(0, 1), a2 + hA, voffA);
;             PG8_WAIT_L(8); PG8_BAR; PG8_WAIT_L(0); PG8_MMA(0, 0, At, B0); PG8_BAR; PG8_SCHED;
;             PG8_LDB(B1, 1, 1); PG8_STAGE(PG8_SB(1, 0), b3, voffB);
;             PG8_BAR; PG8_WAIT_L(0); PG8_MMA(0, 1, At, B1); PG8_BAR;
;             PG8_LDA(At, 1, 1); PG8_STAGE(PG8_SA(1, 0), a3, voffA);
;             PG8_BAR; PG8_WAIT_L(0); PG8_MMA(1, 0, At, B0); PG8_BAR; PG8_SCHED;
;             PG8_STAGE(PG8_SB(1, 1), b3 + hB, voffB);
;             PG8_WAIT_V(6); PG8_BAR; PG8_MMA(1, 1, At, B1); PG8_BAR;
;         }
;         E(acc, cur, wr, wc, fr, fq);
;         if (!has_next) break;
; #pragma unroll
;         for (int a = 0; a < 2; ++a)
; #pragma unroll
;             for (int b = 0; b < 2; ++b)
; #pragma unroll
;                 for (int m = 0; m < 4; ++m)
; #pragma unroll
;                     for (int n = 0; n < 2; ++n) acc[a][b][m][n] = (f32x4){0.f, 0.f, 0.f, 0.f};
;         cur = nxt; cA = nA; cB = nB; ++ui;
.LBB0_836:
	s_ashr_i32 s59, s58, 31
	s_lshl_b64 s[64:65], s[58:59], 19
	s_add_u32 s64, s96, s64
	s_addc_u32 s65, s97, s65
	s_and_b64 s[66:67], s[60:61], exec
	v_mov_b32_e32 v0, 0
	s_cselect_b32 s43, s65, s41
	s_cselect_b32 s59, s64, s40
	s_mov_b32 s78, 0
	s_mov_b64 s[70:71], -1
	s_mov_b64 s[66:67], 0
	v_mov_b32_e32 v1, v0
	v_mov_b64_e32 v[2:3], 0
	v_mov_b64_e32 v[4:5], 0
	v_mov_b64_e32 v[6:7], 0
	v_mov_b64_e32 v[8:9], 0
	v_mov_b64_e32 v[10:11], 0
	v_mov_b64_e32 v[12:13], 0
	v_mov_b64_e32 v[14:15], 0
	v_mov_b64_e32 v[16:17], 0
	v_mov_b64_e32 v[18:19], 0
	v_mov_b64_e32 v[20:21], 0
	v_mov_b64_e32 v[22:23], 0
	v_mov_b64_e32 v[24:25], 0
	v_mov_b64_e32 v[26:27], 0
	v_mov_b64_e32 v[28:29], 0
	v_mov_b64_e32 v[30:31], 0
	v_mov_b64_e32 v[32:33], 0
	v_mov_b64_e32 v[34:35], 0
	v_mov_b64_e32 v[36:37], 0
	v_mov_b64_e32 v[38:39], 0
	v_mov_b64_e32 v[40:41], 0
	v_mov_b64_e32 v[42:43], 0
	v_mov_b64_e32 v[44:45], 0
	v_mov_b64_e32 v[46:47], 0
	v_mov_b64_e32 v[48:49], 0
	v_mov_b64_e32 v[50:51], 0
	v_mov_b64_e32 v[52:53], 0
	v_mov_b64_e32 v[54:55], 0
	v_mov_b64_e32 v[56:57], 0
	v_mov_b64_e32 v[58:59], 0
	v_mov_b64_e32 v[60:61], 0
	v_mov_b64_e32 v[62:63], 0
	v_mov_b64_e32 v[64:65], 0
	v_mov_b64_e32 v[66:67], 0
	v_mov_b64_e32 v[68:69], 0
	v_mov_b64_e32 v[70:71], 0
	v_mov_b64_e32 v[72:73], 0
	v_mov_b64_e32 v[74:75], 0
	v_mov_b64_e32 v[76:77], 0
	v_mov_b64_e32 v[78:79], 0
	v_mov_b64_e32 v[80:81], 0
	v_mov_b64_e32 v[82:83], 0
	v_mov_b64_e32 v[84:85], 0
	v_mov_b64_e32 v[86:87], 0
	v_mov_b64_e32 v[88:89], 0
	v_mov_b64_e32 v[90:91], 0
	v_mov_b64_e32 v[92:93], 0
	v_mov_b64_e32 v[94:95], 0
	v_mov_b64_e32 v[96:97], 0
	v_mov_b64_e32 v[98:99], 0
	v_mov_b64_e32 v[100:101], 0
	v_mov_b64_e32 v[102:103], 0
	v_mov_b64_e32 v[104:105], 0
	v_mov_b64_e32 v[106:107], 0
	v_mov_b64_e32 v[108:109], 0
	v_mov_b64_e32 v[110:111], 0
	v_mov_b64_e32 v[112:113], 0
	v_mov_b64_e32 v[114:115], 0
	v_mov_b64_e32 v[116:117], 0
	v_mov_b64_e32 v[118:119], 0
	v_mov_b64_e32 v[120:121], 0
	v_mov_b64_e32 v[122:123], 0
	v_mov_b64_e32 v[124:125], 0
	v_mov_b64_e32 v[126:127], 0
	s_branch .LBB0_840

; #define PG8_WAIT_V(n) asm volatile("s_waitcnt vmcnt(" #n ")" ::: "memory")
;     ...
;         const bool has_next = S.next(ui + 1, nxt);
;         const char* nA = has_next ? (const char*)g.A + (size_t)nxt.pm * tA : cA; const char* nB = has_next ? (const char*)g.Bt + (size_t)nxt.pn * tB : cB;
; #pragma unroll 1
;         for (int t = 0; t < nt; t += 2) {
;             const bool last = (t == nt - 2);
;             const char* a1 = cA + (size_t)(t + 1) * kstep;
;             const char* a2 = last ? nA : cA + (size_t)(t + 2) * kstep; const char* b2 = last ? nB : cB + (size_t)(t + 2) * kstep;
;             const char* a3 = a2 + kstep; const char* b3 = b2 + kstep;
;             if (last && has_next) PG8_A_READY(nxt);
;             PG8_LDB(B0, 0, 0); PG8_SCHED; PG8_LDA(At, 0, 0); PG8_STAGE(PG8_SA(1, 1), a1 + hA, voffA);
;             PG8_WAIT_L(8); PG8_BAR; PG8_WAIT_L(0); PG8_MMA(0, 0, At, B0); PG8_BAR; PG8_SCHED;
;             PG8_LDB(B1, 0, 1); PG8_STAGE(PG8_SB(0, 0), b2, voffB);
;             PG8_BAR; PG8_WAIT_L(0); PG8_MMA(0, 1, At, B1); PG8_BAR;
;             PG8_LDA(At, 0, 1); PG8_STAGE(PG8_SA(0, 0), a2, voffA);
;             PG8_BAR; PG8_WAIT_L(0); PG8_MMA(1, 0, At, B0); PG8_BAR; PG8_SCHED;
;             PG8_STAGE(PG8_SB(0, 1), b2 + hB, voffB);
;             PG8_WAIT_V(6); PG8_BAR; PG8_MMA(1, 1, At, B1); PG8_BAR;
;             PG8_LDB(B0, 1, 0); PG8_SCHED; PG8_LDA(At, 1, 0); PG8_STAGE(PG8_SA(0, 1), a2 + hA, voffA);
;             PG8_WAIT_L(8); PG8_BAR; PG8_WAIT_L(0); PG8_MMA(0, 0, At, B0); PG8_BAR; PG8_SCHED;
;             PG8_LDB(B1, 1, 1); PG8_STAGE(PG8_SB(1, 0), b3, voffB);
;             PG8_BAR; PG8_WAIT_L(0); PG8_MMA(0, 1, At, B1); PG8_BAR;
;             PG8_LDA(At, 1, 1); PG8_STAGE(PG8_SA(1, 0), a3, voffA);
;             PG8_BAR; PG8_WAIT_L(0); PG8_MMA(1, 0, At, B0); PG8_BAR; PG8_SCHED;
;             PG8_STAGE(PG8_SB(1, 1), b3 + hB, voffB);
;             PG8_WAIT_V(6); PG8_BAR; PG8_MMA(1, 1, At, B1); PG8_BAR;
;         }
;         E(acc, cur, wr, wc, fr, fq);
;         if (!has_next) break;
; #pragma unroll
;         for (int a = 0; a < 2; ++a)
; #pragma unroll
;             for (int b = 0; b < 2; ++b)
; #pragma unroll
;                 for (int m = 0; m < 4; ++m)
; #pragma unroll
;                     for (int n = 0; n < 2; ++n) acc[a][b][m][n] = (f32x4){0.f, 0.f, 0.f, 0.f};
;         cur = nxt; cA = nA; cB = nB; ++ui;
.LBB0_957:
	s_ashr_i32 s29, s28, 31
	s_lshl_b64 s[8:9], s[28:29], 19
	s_add_u32 s36, s14, s8
	v_cmp_lt_i64_e32 vcc, s[34:35], v[140:141]
	s_addc_u32 s37, s15, s9
	s_and_b64 s[8:9], vcc, exec
	s_cselect_b32 s7, s37, s41
	s_cselect_b32 s8, s36, s40
	s_ashr_i32 s39, s38, 31
	s_lshl_b64 s[34:35], s[38:39], 19
	s_add_u32 s34, s24, s34
	s_addc_u32 s35, s25, s35
	s_and_b64 s[42:43], vcc, exec
	s_cselect_b32 s9, s35, s55
	s_cselect_b32 s29, s34, s54
	s_add_u32 s33, s54, 0x100
	s_addc_u32 s39, s55, 0
	s_add_u32 s40, s40, 0x40080
	v_mov_b32_e32 v0, 0
	s_addc_u32 s41, s41, 0
	s_mov_b32 s42, -2
	v_mov_b32_e32 v1, v0
	v_mov_b64_e32 v[2:3], 0
	v_mov_b64_e32 v[4:5], 0
	v_mov_b64_e32 v[6:7], 0
	v_mov_b64_e32 v[8:9], 0
	v_mov_b64_e32 v[10:11], 0
	v_mov_b64_e32 v[12:13], 0
	v_mov_b64_e32 v[14:15], 0
	v_mov_b64_e32 v[16:17], 0
	v_mov_b64_e32 v[18:19], 0
	v_mov_b64_e32 v[20:21], 0
	v_mov_b64_e32 v[22:23], 0
	v_mov_b64_e32 v[24:25], 0
	v_mov_b64_e32 v[26:27], 0
	v_mov_b64_e32 v[28:29], 0
	v_mov_b64_e32 v[30:31], 0
	v_mov_b64_e32 v[32:33], 0
	v_mov_b64_e32 v[34:35], 0
	v_mov_b64_e32 v[36:37], 0
	v_mov_b64_e32 v[38:39], 0
	v_mov_b64_e32 v[40:41], 0
	v_mov_b64_e32 v[42:43], 0
	v_mov_b64_e32 v[44:45], 0
	v_mov_b64_e32 v[46:47], 0
	v_mov_b64_e32 v[48:49], 0
	v_mov_b64_e32 v[50:51], 0
	v_mov_b64_e32 v[52:53], 0
	v_mov_b64_e32 v[54:55], 0
	v_mov_b64_e32 v[56:57], 0
	v_mov_b64_e32 v[58:59], 0
	v_mov_b64_e32 v[60:61], 0
	v_mov_b64_e32 v[62:63], 0
	v_mov_b64_e32 v[64:65], 0
	v_mov_b64_e32 v[66:67], 0
	v_mov_b64_e32 v[68:69], 0
	v_mov_b64_e32 v[70:71], 0
	v_mov_b64_e32 v[72:73], 0
	v_mov_b64_e32 v[74:75], 0
	v_mov_b64_e32 v[76:77], 0
	v_mov_b64_e32 v[78:79], 0
	v_mov_b64_e32 v[80:81], 0
	v_mov_b64_e32 v[82:83], 0
	v_mov_b64_e32 v[84:85], 0
	v_mov_b64_e32 v[86:87], 0
	v_mov_b64_e32 v[88:89], 0
	v_mov_b64_e32 v[90:91], 0
	v_mov_b64_e32 v[92:93], 0
	v_mov_b64_e32 v[94:95], 0
	v_mov_b64_e32 v[96:97], 0
	v_mov_b64_e32 v[98:99], 0
	v_mov_b64_e32 v[100:101], 0
	v_mov_b64_e32 v[102:103], 0
	v_mov_b64_e32 v[104:105], 0
	v_mov_b64_e32 v[106:107], 0
	v_mov_b64_e32 v[108:109], 0
	v_mov_b64_e32 v[110:111], 0
	v_mov_b64_e32 v[112:113], 0
	v_mov_b64_e32 v[114:115], 0
	v_mov_b64_e32 v[116:117], 0
	v_mov_b64_e32 v[118:119], 0
	v_mov_b64_e32 v[120:121], 0
	v_mov_b64_e32 v[122:123], 0
	v_mov_b64_e32 v[124:125], 0
	v_mov_b64_e32 v[126:127], 0

; #define PG8_WAIT_V(n) asm volatile("s_waitcnt vmcnt(" #n ")" ::: "memory")
;     ...
;         const bool has_next = S.next(ui + 1, nxt);
;         const char* nA = has_next ? (const char*)g.A + (size_t)nxt.pm * tA : cA; const char* nB = has_next ? (const char*)g.Bt + (size_t)nxt.pn * tB : cB;
; #pragma unroll 1
;         for (int t = 0; t < nt; t += 2) {
;             const bool last = (t == nt - 2);
;             const char* a1 = cA + (size_t)(t + 1) * kstep;
;             const char* a2 = last ? nA : cA + (size_t)(t + 2) * kstep; const char* b2 = last ? nB : cB + (size_t)(t + 2) * kstep;
;             const char* a3 = a2 + kstep; const char* b3 = b2 + kstep;
;             if (last && has_next) PG8_A_READY(nxt);
;             PG8_LDB(B0, 0, 0); PG8_SCHED; PG8_LDA(At, 0, 0); PG8_STAGE(PG8_SA(1, 1), a1 + hA, voffA);
;             PG8_WAIT_L(8); PG8_BAR; PG8_WAIT_L(0); PG8_MMA(0, 0, At, B0); PG8_BAR; PG8_SCHED;
;             PG8_LDB(B1, 0, 1); PG8_STAGE(PG8_SB(0, 0), b2, voffB);
;             PG8_BAR; PG8_WAIT_L(0); PG8_MMA(0, 1, At, B1); PG8_BAR;
;             PG8_LDA(At, 0, 1); PG8_STAGE(PG8_SA(0, 0), a2, voffA);
;             PG8_BAR; PG8_WAIT_L(0); PG8_MMA(1, 0, At, B0); PG8_BAR; PG8_SCHED;
;             PG8_STAGE(PG8_SB(0, 1), b2 + hB, voffB);
;             PG8_WAIT_V(6); PG8_BAR; PG8_MMA(1, 1, At, B1); PG8_BAR;
;             PG8_LDB(B0, 1, 0); PG8_SCHED; PG8_LDA(At, 1, 0); PG8_STAGE(PG8_SA(0, 1), a2 + hA, voffA);
;             PG8_WAIT_L(8); PG8_BAR; PG8_WAIT_L(0); PG8_MMA(0, 0, At, B0); PG8_BAR; PG8_SCHED;
;             PG8_LDB(B1, 1, 1); PG8_STAGE(PG8_SB(1, 0), b3, voffB);
;             PG8_BAR; PG8_WAIT_L(0); PG8_MMA(0, 1, At, B1); PG8_BAR;
;             PG8_LDA(At, 1, 1); PG8_STAGE(PG8_SA(1, 0), a3, voffA);
;             PG8_BAR; PG8_WAIT_L(0); PG8_MMA(1, 0, At, B0); PG8_BAR; PG8_SCHED;
;             PG8_STAGE(PG8_SB(1, 1), b3 + hB, voffB);
;             PG8_WAIT_V(6); PG8_BAR; PG8_MMA(1, 1, At, B1); PG8_BAR;
;         }
;         E(acc, cur, wr, wc, fr, fq);
;         if (!has_next) break;
; #pragma unroll
;         for (int a = 0; a < 2; ++a)
; #pragma unroll
;             for (int b = 0; b < 2; ++b)
; #pragma unroll
;                 for (int m = 0; m < 4; ++m)
; #pragma unroll
;                     for (int n = 0; n < 2; ++n) acc[a][b][m][n] = (f32x4){0.f, 0.f, 0.f, 0.f};
;         cur = nxt; cA = nA; cB = nB; ++ui;
.LBB0_980:
	s_ashr_i32 s25, s24, 31
	s_lshl_b64 s[8:9], s[24:25], 19
	s_add_u32 s30, s58, s8
	v_cmp_lt_i64_e64 s[54:55], s[28:29], 64
	s_addc_u32 s31, s59, s9
	s_and_b64 s[8:9], s[54:55], exec
	s_cselect_b32 s7, s31, s39
	s_cselect_b32 s8, s30, s38
	s_ashr_i32 s35, s34, 31
	s_lshl_b64 s[28:29], s[34:35], 19
	s_add_u32 s28, s16, s28
	s_addc_u32 s29, s17, s29
	s_and_b64 s[42:43], s[54:55], exec
	s_cselect_b32 s9, s29, s41
	s_cselect_b32 s25, s28, s40
	s_add_u32 s33, s40, 0x100
	s_addc_u32 s35, s41, 0
	s_add_u32 s38, s38, 0x40080
	v_mov_b32_e32 v0, 0
	s_addc_u32 s39, s39, 0
	s_mov_b32 s42, -2
	v_mov_b32_e32 v1, v0
	v_mov_b64_e32 v[2:3], 0
	v_mov_b64_e32 v[4:5], 0
	v_mov_b64_e32 v[6:7], 0
	v_mov_b64_e32 v[8:9], 0
	v_mov_b64_e32 v[10:11], 0
	v_mov_b64_e32 v[12:13], 0
	v_mov_b64_e32 v[14:15], 0
	v_mov_b64_e32 v[16:17], 0
	v_mov_b64_e32 v[18:19], 0
	v_mov_b64_e32 v[20:21], 0
	v_mov_b64_e32 v[22:23], 0
	v_mov_b64_e32 v[24:25], 0
	v_mov_b64_e32 v[26:27], 0
	v_mov_b64_e32 v[28:29], 0
	v_mov_b64_e32 v[30:31], 0
	v_mov_b64_e32 v[32:33], 0
	v_mov_b64_e32 v[34:35], 0
	v_mov_b64_e32 v[36:37], 0
	v_mov_b64_e32 v[38:39], 0
	v_mov_b64_e32 v[40:41], 0
	v_mov_b64_e32 v[42:43], 0
	v_mov_b64_e32 v[44:45], 0
	v_mov_b64_e32 v[46:47], 0
	v_mov_b64_e32 v[48:49], 0
	v_mov_b64_e32 v[50:51], 0
	v_mov_b64_e32 v[52:53], 0
	v_mov_b64_e32 v[54:55], 0
	v_mov_b64_e32 v[56:57], 0
	v_mov_b64_e32 v[58:59], 0
	v_mov_b64_e32 v[60:61], 0
	v_mov_b64_e32 v[62:63], 0
	v_mov_b64_e32 v[64:65], 0
	v_mov_b64_e32 v[66:67], 0
	v_mov_b64_e32 v[68:69], 0
	v_mov_b64_e32 v[70:71], 0
	v_mov_b64_e32 v[72:73], 0
	v_mov_b64_e32 v[74:75], 0
	v_mov_b64_e32 v[76:77], 0
	v_mov_b64_e32 v[78:79], 0
	v_mov_b64_e32 v[80:81], 0
	v_mov_b64_e32 v[82:83], 0
	v_mov_b64_e32 v[84:85], 0
	v_mov_b64_e32 v[86:87], 0
	v_mov_b64_e32 v[88:89], 0
	v_mov_b64_e32 v[90:91], 0
	v_mov_b64_e32 v[92:93], 0
	v_mov_b64_e32 v[94:95], 0
	v_mov_b64_e32 v[96:97], 0
	v_mov_b64_e32 v[98:99], 0
	v_mov_b64_e32 v[100:101], 0
	v_mov_b64_e32 v[102:103], 0
	v_mov_b64_e32 v[104:105], 0
	v_mov_b64_e32 v[106:107], 0
	v_mov_b64_e32 v[108:109], 0
	v_mov_b64_e32 v[110:111], 0
	v_mov_b64_e32 v[112:113], 0
	v_mov_b64_e32 v[114:115], 0
	v_mov_b64_e32 v[116:117], 0
	v_mov_b64_e32 v[118:119], 0
	v_mov_b64_e32 v[120:121], 0
	v_mov_b64_e32 v[122:123], 0
	v_mov_b64_e32 v[124:125], 0
	v_mov_b64_e32 v[126:127], 0

; #define PG8_WAIT_V(n) asm volatile("s_waitcnt vmcnt(" #n ")" ::: "memory")
;     ...
;         const bool has_next = S.next(ui + 1, nxt);
;         const char* nA = has_next ? (const char*)g.A + (size_t)nxt.pm * tA : cA; const char* nB = has_next ? (const char*)g.Bt + (size_t)nxt.pn * tB : cB;
; #pragma unroll 1
;         for (int t = 0; t < nt; t += 2) {
;             const bool last = (t == nt - 2);
;             const char* a1 = cA + (size_t)(t + 1) * kstep;
;             const char* a2 = last ? nA : cA + (size_t)(t + 2) * kstep; const char* b2 = last ? nB : cB + (size_t)(t + 2) * kstep;
;             const char* a3 = a2 + kstep; const char* b3 = b2 + kstep;
;             if (last && has_next) PG8_A_READY(nxt);
;             PG8_LDB(B0, 0, 0); PG8_SCHED; PG8_LDA(At, 0, 0); PG8_STAGE(PG8_SA(1, 1), a1 + hA, voffA);
;             PG8_WAIT_L(8); PG8_BAR; PG8_WAIT_L(0); PG8_MMA(0, 0, At, B0); PG8_BAR; PG8_SCHED;
;             PG8_LDB(B1, 0, 1); PG8_STAGE(PG8_SB(0, 0), b2, voffB);
;             PG8_BAR; PG8_WAIT_L(0); PG8_MMA(0, 1, At, B1); PG8_BAR;
;             PG8_LDA(At, 0, 1); PG8_STAGE(PG8_SA(0, 0), a2, voffA);
;             PG8_BAR; PG8_WAIT_L(0); PG8_MMA(1, 0, At, B0); PG8_BAR; PG8_SCHED;
;             PG8_STAGE(PG8_SB(0, 1), b2 + hB, voffB);
;             PG8_WAIT_V(6); PG8_BAR; PG8_MMA(1, 1, At, B1); PG8_BAR;
;             PG8_LDB(B0, 1, 0); PG8_SCHED; PG8_LDA(At, 1, 0); PG8_STAGE(PG8_SA(0, 1), a2 + hA, voffA);
;             PG8_WAIT_L(8); PG8_BAR; PG8_WAIT_L(0); PG8_MMA(0, 0, At, B0); PG8_BAR; PG8_SCHED;
;             PG8_LDB(B1, 1, 1); PG8_STAGE(PG8_SB(1, 0), b3, voffB);
;             PG8_BAR; PG8_WAIT_L(0); PG8_MMA(0, 1, At, B1); PG8_BAR;
;             PG8_LDA(At, 1, 1); PG8_STAGE(PG8_SA(1, 0), a3, voffA);
;             PG8_BAR; PG8_WAIT_L(0); PG8_MMA(1, 0, At, B0); PG8_BAR; PG8_SCHED;
;             PG8_STAGE(PG8_SB(1, 1), b3 + hB, voffB);
;             PG8_WAIT_V(6); PG8_BAR; PG8_MMA(1, 1, At, B1); PG8_BAR;
;         }
;         E(acc, cur, wr, wc, fr, fq);
;         if (!has_next) break;
; #pragma unroll
;         for (int a = 0; a < 2; ++a)
; #pragma unroll
;             for (int b = 0; b < 2; ++b)
; #pragma unroll
;                 for (int m = 0; m < 4; ++m)
; #pragma unroll
;                     for (int n = 0; n < 2; ++n) acc[a][b][m][n] = (f32x4){0.f, 0.f, 0.f, 0.f};
;         cur = nxt; cA = nA; cB = nB; ++ui;
.LBB0_1019:
	s_ashr_i32 s39, s38, 31
	s_lshl_b64 s[6:7], s[38:39], 21
	s_add_u32 s40, s18, s6
	s_addc_u32 s41, s19, s7
	s_and_b64 s[6:7], s[16:17], exec
	s_cselect_b32 s6, s41, s61
	s_cselect_b32 s7, s40, s60
	s_ashr_i32 s37, s36, 31
	s_lshl_b64 s[8:9], s[36:37], 21
	s_add_u32 s54, s24, s8
	s_addc_u32 s55, s25, s9
	s_and_b64 s[8:9], s[16:17], exec
	s_cselect_b32 s8, s55, s63
	s_cselect_b32 s9, s54, s62
	s_add_u32 s33, s60, 0x100000
	s_addc_u32 s37, s61, 0
	s_lshl_b32 s42, s38, 6
	s_ashr_i32 s43, s42, 31
	s_lshl_b64 s[42:43], s[42:43], 2
	s_add_u32 s64, s73, s42
	v_mov_b32_e32 v0, 0
	s_addc_u32 s65, s74, s43
	s_mov_b32 s39, 0
	s_waitcnt lgkmcnt(0)
	v_mov_b32_e32 v1, v0
	v_mov_b64_e32 v[2:3], 0
	v_mov_b64_e32 v[4:5], 0
	v_mov_b64_e32 v[6:7], 0
	v_mov_b64_e32 v[8:9], 0
	v_mov_b64_e32 v[10:11], 0
	v_mov_b64_e32 v[12:13], 0
	v_mov_b64_e32 v[14:15], 0
	v_mov_b64_e32 v[16:17], 0
	v_mov_b64_e32 v[18:19], 0
	v_mov_b64_e32 v[20:21], 0
	v_mov_b64_e32 v[22:23], 0
	v_mov_b64_e32 v[24:25], 0
	v_mov_b64_e32 v[26:27], 0
	v_mov_b64_e32 v[28:29], 0
	v_mov_b64_e32 v[30:31], 0
	v_mov_b64_e32 v[32:33], 0
	v_mov_b64_e32 v[34:35], 0
	v_mov_b64_e32 v[36:37], 0
	v_mov_b64_e32 v[38:39], 0
	v_mov_b64_e32 v[40:41], 0
	v_mov_b64_e32 v[42:43], 0
	v_mov_b64_e32 v[44:45], 0
	v_mov_b64_e32 v[46:47], 0
	v_mov_b64_e32 v[48:49], 0
	v_mov_b64_e32 v[50:51], 0
	v_mov_b64_e32 v[52:53], 0
	v_mov_b64_e32 v[54:55], 0
	v_mov_b64_e32 v[56:57], 0
	v_mov_b64_e32 v[58:59], 0
	v_mov_b64_e32 v[60:61], 0
	v_mov_b64_e32 v[62:63], 0
	v_mov_b64_e32 v[64:65], 0
	v_mov_b64_e32 v[66:67], 0
	v_mov_b64_e32 v[68:69], 0
	v_mov_b64_e32 v[70:71], 0
	v_mov_b64_e32 v[72:73], 0
	v_mov_b64_e32 v[74:75], 0
	v_mov_b64_e32 v[76:77], 0
	v_mov_b64_e32 v[78:79], 0
	v_mov_b64_e32 v[80:81], 0
	v_mov_b64_e32 v[82:83], 0
	v_mov_b64_e32 v[84:85], 0
	v_mov_b64_e32 v[86:87], 0
	v_mov_b64_e32 v[88:89], 0
	v_mov_b64_e32 v[90:91], 0
	v_mov_b64_e32 v[92:93], 0
	v_mov_b64_e32 v[94:95], 0
	v_mov_b64_e32 v[96:97], 0
	v_mov_b64_e32 v[98:99], 0
	v_mov_b64_e32 v[100:101], 0
	v_mov_b64_e32 v[102:103], 0
	v_mov_b64_e32 v[104:105], 0
	v_mov_b64_e32 v[106:107], 0
	v_mov_b64_e32 v[108:109], 0
	v_mov_b64_e32 v[110:111], 0
	v_mov_b64_e32 v[112:113], 0
	v_mov_b64_e32 v[114:115], 0
	v_mov_b64_e32 v[116:117], 0
	v_mov_b64_e32 v[118:119], 0
	v_mov_b64_e32 v[120:121], 0
	v_mov_b64_e32 v[122:123], 0
	v_mov_b64_e32 v[124:125], 0
	v_mov_b64_e32 v[126:127], 0
	s_branch .LBB0_1023

; #define PG8_WAIT_V(n) asm volatile("s_waitcnt vmcnt(" #n ")" ::: "memory")
;     ...
;         const bool has_next = S.next(ui + 1, nxt);
;         const char* nA = has_next ? (const char*)g.A + (size_t)nxt.pm * tA : cA; const char* nB = has_next ? (const char*)g.Bt + (size_t)nxt.pn * tB : cB;
; #pragma unroll 1
;         for (int t = 0; t < nt; t += 2) {
;             const bool last = (t == nt - 2);
;             const char* a1 = cA + (size_t)(t + 1) * kstep;
;             const char* a2 = last ? nA : cA + (size_t)(t + 2) * kstep; const char* b2 = last ? nB : cB + (size_t)(t + 2) * kstep;
;             const char* a3 = a2 + kstep; const char* b3 = b2 + kstep;
;             if (last && has_next) PG8_A_READY(nxt);
;             PG8_LDB(B0, 0, 0); PG8_SCHED; PG8_LDA(At, 0, 0); PG8_STAGE(PG8_SA(1, 1), a1 + hA, voffA);
;             PG8_WAIT_L(8); PG8_BAR; PG8_WAIT_L(0); PG8_MMA(0, 0, At, B0); PG8_BAR; PG8_SCHED;
;             PG8_LDB(B1, 0, 1); PG8_STAGE(PG8_SB(0, 0), b2, voffB);
;             PG8_BAR; PG8_WAIT_L(0); PG8_MMA(0, 1, At, B1); PG8_BAR;
;             PG8_LDA(At, 0, 1); PG8_STAGE(PG8_SA(0, 0), a2, voffA);
;             PG8_BAR; PG8_WAIT_L(0); PG8_MMA(1, 0, At, B0); PG8_BAR; PG8_SCHED;
;             PG8_STAGE(PG8_SB(0, 1), b2 + hB, voffB);
;             PG8_WAIT_V(6); PG8_BAR; PG8_MMA(1, 1, At, B1); PG8_BAR;
;             PG8_LDB(B0, 1, 0); PG8_SCHED; PG8_LDA(At, 1, 0); PG8_STAGE(PG8_SA(0, 1), a2 + hA, voffA);
;             PG8_WAIT_L(8); PG8_BAR; PG8_WAIT_L(0); PG8_MMA(0, 0, At, B0); PG8_BAR; PG8_SCHED;
;             PG8_LDB(B1, 1, 1); PG8_STAGE(PG8_SB(1, 0), b3, voffB);
;             PG8_BAR; PG8_WAIT_L(0); PG8_MMA(0, 1, At, B1); PG8_BAR;
;             PG8_LDA(At, 1, 1); PG8_STAGE(PG8_SA(1, 0), a3, voffA);
;             PG8_BAR; PG8_WAIT_L(0); PG8_MMA(1, 0, At, B0); PG8_BAR; PG8_SCHED;
;             PG8_STAGE(PG8_SB(1, 1), b3 + hB, voffB);
;             PG8_WAIT_V(6); PG8_BAR; PG8_MMA(1, 1, At, B1); PG8_BAR;
;         }
;         E(acc, cur, wr, wc, fr, fq);
;         if (!has_next) break;
; #pragma unroll
;         for (int a = 0; a < 2; ++a)
; #pragma unroll
;             for (int b = 0; b < 2; ++b)
; #pragma unroll
;                 for (int m = 0; m < 4; ++m)
; #pragma unroll
;                     for (int n = 0; n < 2; ++n) acc[a][b][m][n] = (f32x4){0.f, 0.f, 0.f, 0.f};
;         cur = nxt; cA = nA; cB = nB; ++ui;
.LBB0_1088:
	s_ashr_i32 s55, s54, 31
	s_lshl_b64 s[8:9], s[54:55], 21
	s_add_u32 s56, s87, s8
	s_addc_u32 s57, s88, s9
	s_and_b64 s[8:9], s[58:59], exec
	s_cselect_b32 s8, s57, s31
	s_cselect_b32 s9, s56, s30
	s_ashr_i32 s41, s40, 31
	s_lshl_b64 s[42:43], s[40:41], 21
	s_add_u32 s60, s89, s42
	s_addc_u32 s61, s90, s43
	s_and_b64 s[42:43], s[58:59], exec
	s_cselect_b32 s41, s61, s35
	s_cselect_b32 s42, s60, s34
	s_add_u32 s43, s30, 0x100000
	s_addc_u32 s45, s31, 0
	s_lshl_b32 s62, s54, 6
	s_ashr_i32 s63, s62, 31
	s_lshl_b64 s[62:63], s[62:63], 2
	s_add_u32 s62, s73, s62
	v_mov_b32_e32 v0, 0
	s_addc_u32 s63, s74, s63
	s_mov_b32 s55, 0
	v_mov_b32_e32 v1, v0
	v_mov_b64_e32 v[2:3], 0
	v_mov_b64_e32 v[4:5], 0
	v_mov_b64_e32 v[6:7], 0
	v_mov_b64_e32 v[8:9], 0
	v_mov_b64_e32 v[10:11], 0
	v_mov_b64_e32 v[12:13], 0
	v_mov_b64_e32 v[14:15], 0
	v_mov_b64_e32 v[16:17], 0
	v_mov_b64_e32 v[18:19], 0
	v_mov_b64_e32 v[20:21], 0
	v_mov_b64_e32 v[22:23], 0
	v_mov_b64_e32 v[24:25], 0
	v_mov_b64_e32 v[26:27], 0
	v_mov_b64_e32 v[28:29], 0
	v_mov_b64_e32 v[30:31], 0
	v_mov_b64_e32 v[32:33], 0
	v_mov_b64_e32 v[34:35], 0
	v_mov_b64_e32 v[36:37], 0
	v_mov_b64_e32 v[38:39], 0
	v_mov_b64_e32 v[40:41], 0
	v_mov_b64_e32 v[42:43], 0
	v_mov_b64_e32 v[44:45], 0
	v_mov_b64_e32 v[46:47], 0
	v_mov_b64_e32 v[48:49], 0
	v_mov_b64_e32 v[50:51], 0
	v_mov_b64_e32 v[52:53], 0
	v_mov_b64_e32 v[54:55], 0
	v_mov_b64_e32 v[56:57], 0
	v_mov_b64_e32 v[58:59], 0
	v_mov_b64_e32 v[60:61], 0
	v_mov_b64_e32 v[62:63], 0
	v_mov_b64_e32 v[64:65], 0
	v_mov_b64_e32 v[66:67], 0
	v_mov_b64_e32 v[68:69], 0
	v_mov_b64_e32 v[70:71], 0
	v_mov_b64_e32 v[72:73], 0
	v_mov_b64_e32 v[74:75], 0
	v_mov_b64_e32 v[76:77], 0
	v_mov_b64_e32 v[78:79], 0
	v_mov_b64_e32 v[80:81], 0
	v_mov_b64_e32 v[82:83], 0
	v_mov_b64_e32 v[84:85], 0
	v_mov_b64_e32 v[86:87], 0
	v_mov_b64_e32 v[88:89], 0
	v_mov_b64_e32 v[90:91], 0
	v_mov_b64_e32 v[92:93], 0
	v_mov_b64_e32 v[94:95], 0
	v_mov_b64_e32 v[96:97], 0
	v_mov_b64_e32 v[98:99], 0
	v_mov_b64_e32 v[100:101], 0
	v_mov_b64_e32 v[102:103], 0
	v_mov_b64_e32 v[104:105], 0
	v_mov_b64_e32 v[106:107], 0
	v_mov_b64_e32 v[108:109], 0
	v_mov_b64_e32 v[110:111], 0
	v_mov_b64_e32 v[112:113], 0
	v_mov_b64_e32 v[114:115], 0
	v_mov_b64_e32 v[116:117], 0
	v_mov_b64_e32 v[118:119], 0
	v_mov_b64_e32 v[120:121], 0
	v_mov_b64_e32 v[122:123], 0
	v_mov_b64_e32 v[124:125], 0
	v_mov_b64_e32 v[126:127], 0
	s_branch .LBB0_1092

; #define PG8_WAIT_V(n) asm volatile("s_waitcnt vmcnt(" #n ")" ::: "memory")
;     ...
;         const bool has_next = S.next(ui + 1, nxt);
;         const char* nA = has_next ? (const char*)g.A + (size_t)nxt.pm * tA : cA; const char* nB = has_next ? (const char*)g.Bt + (size_t)nxt.pn * tB : cB;
; #pragma unroll 1
;         for (int t = 0; t < nt; t += 2) {
;             const bool last = (t == nt - 2);
;             const char* a1 = cA + (size_t)(t + 1) * kstep;
;             const char* a2 = last ? nA : cA + (size_t)(t + 2) * kstep; const char* b2 = last ? nB : cB + (size_t)(t + 2) * kstep;
;             const char* a3 = a2 + kstep; const char* b3 = b2 + kstep;
;             if (last && has_next) PG8_A_READY(nxt);
;             PG8_LDB(B0, 0, 0); PG8_SCHED; PG8_LDA(At, 0, 0); PG8_STAGE(PG8_SA(1, 1), a1 + hA, voffA);
;             PG8_WAIT_L(8); PG8_BAR; PG8_WAIT_L(0); PG8_MMA(0, 0, At, B0); PG8_BAR; PG8_SCHED;
;             PG8_LDB(B1, 0, 1); PG8_STAGE(PG8_SB(0, 0), b2, voffB);
;             PG8_BAR; PG8_WAIT_L(0); PG8_MMA(0, 1, At, B1); PG8_BAR;
;             PG8_LDA(At, 0, 1); PG8_STAGE(PG8_SA(0, 0), a2, voffA);
;             PG8_BAR; PG8_WAIT_L(0); PG8_MMA(1, 0, At, B0); PG8_BAR; PG8_SCHED;
;             PG8_STAGE(PG8_SB(0, 1), b2 + hB, voffB);
;             PG8_WAIT_V(6); PG8_BAR; PG8_MMA(1, 1, At, B1); PG8_BAR;
;             PG8_LDB(B0, 1, 0); PG8_SCHED; PG8_LDA(At, 1, 0); PG8_STAGE(PG8_SA(0, 1), a2 + hA, voffA);
;             PG8_WAIT_L(8); PG8_BAR; PG8_WAIT_L(0); PG8_MMA(0, 0, At, B0); PG8_BAR; PG8_SCHED;
;             PG8_LDB(B1, 1, 1); PG8_STAGE(PG8_SB(1, 0), b3, voffB);
;             PG8_BAR; PG8_WAIT_L(0); PG8_MMA(0, 1, At, B1); PG8_BAR;
;             PG8_LDA(At, 1, 1); PG8_STAGE(PG8_SA(1, 0), a3, voffA);
;             PG8_BAR; PG8_WAIT_L(0); PG8_MMA(1, 0, At, B0); PG8_BAR; PG8_SCHED;
;             PG8_STAGE(PG8_SB(1, 1), b3 + hB, voffB);
;             PG8_WAIT_V(6); PG8_BAR; PG8_MMA(1, 1, At, B1); PG8_BAR;
;         }
;         E(acc, cur, wr, wc, fr, fq);
;         if (!has_next) break;
; #pragma unroll
;         for (int a = 0; a < 2; ++a)
; #pragma unroll
;             for (int b = 0; b < 2; ++b)
; #pragma unroll
;                 for (int m = 0; m < 4; ++m)
; #pragma unroll
;                     for (int n = 0; n < 2; ++n) acc[a][b][m][n] = (f32x4){0.f, 0.f, 0.f, 0.f};
;         cur = nxt; cA = nA; cB = nB; ++ui;
.LBB0_1287:
	s_ashr_i32 s25, s24, 31
	s_lshl_b64 s[8:9], s[24:25], 19
	v_cmp_lt_i64_e32 vcc, s[26:27], v[140:141]
	s_add_u32 s26, s12, s8
	s_addc_u32 s27, s13, s9
	s_and_b64 s[8:9], vcc, exec
	s_cselect_b32 s7, s27, s37
	s_cselect_b32 s8, s26, s36
	s_ashr_i32 s23, s22, 31
	s_lshl_b64 s[28:29], s[22:23], 19
	s_add_u32 s28, s14, s28
	s_addc_u32 s29, s15, s29
	s_and_b64 s[38:39], vcc, exec
	s_cselect_b32 s9, s29, s35
	s_cselect_b32 s23, s28, s34
	s_add_u32 s25, s34, 0x100
	s_addc_u32 s33, s35, 0
	s_add_u32 s34, s36, 0x40080
	v_mov_b32_e32 v0, 0
	s_addc_u32 s35, s37, 0
	s_mov_b32 s42, -2
	v_mov_b32_e32 v1, v0
	v_mov_b64_e32 v[2:3], 0
	v_mov_b64_e32 v[4:5], 0
	v_mov_b64_e32 v[6:7], 0
	v_mov_b64_e32 v[8:9], 0
	v_mov_b64_e32 v[10:11], 0
	v_mov_b64_e32 v[12:13], 0
	v_mov_b64_e32 v[14:15], 0
	v_mov_b64_e32 v[16:17], 0
	v_mov_b64_e32 v[18:19], 0
	v_mov_b64_e32 v[20:21], 0
	v_mov_b64_e32 v[22:23], 0
	v_mov_b64_e32 v[24:25], 0
	v_mov_b64_e32 v[26:27], 0
	v_mov_b64_e32 v[28:29], 0
	v_mov_b64_e32 v[30:31], 0
	v_mov_b64_e32 v[32:33], 0
	v_mov_b64_e32 v[34:35], 0
	v_mov_b64_e32 v[36:37], 0
	v_mov_b64_e32 v[38:39], 0
	v_mov_b64_e32 v[40:41], 0
	v_mov_b64_e32 v[42:43], 0
	v_mov_b64_e32 v[44:45], 0
	v_mov_b64_e32 v[46:47], 0
	v_mov_b64_e32 v[48:49], 0
	v_mov_b64_e32 v[50:51], 0
	v_mov_b64_e32 v[52:53], 0
	v_mov_b64_e32 v[54:55], 0
	v_mov_b64_e32 v[56:57], 0
	v_mov_b64_e32 v[58:59], 0
	v_mov_b64_e32 v[60:61], 0
	v_mov_b64_e32 v[62:63], 0
	v_mov_b64_e32 v[64:65], 0
	v_mov_b64_e32 v[66:67], 0
	v_mov_b64_e32 v[68:69], 0
	v_mov_b64_e32 v[70:71], 0
	v_mov_b64_e32 v[72:73], 0
	v_mov_b64_e32 v[74:75], 0
	v_mov_b64_e32 v[76:77], 0
	v_mov_b64_e32 v[78:79], 0
	v_mov_b64_e32 v[80:81], 0
	v_mov_b64_e32 v[82:83], 0
	v_mov_b64_e32 v[84:85], 0
	v_mov_b64_e32 v[86:87], 0
	v_mov_b64_e32 v[88:89], 0
	v_mov_b64_e32 v[90:91], 0
	v_mov_b64_e32 v[92:93], 0
	v_mov_b64_e32 v[94:95], 0
	v_mov_b64_e32 v[96:97], 0
	v_mov_b64_e32 v[98:99], 0
	v_mov_b64_e32 v[100:101], 0
	v_mov_b64_e32 v[102:103], 0
	v_mov_b64_e32 v[104:105], 0
	v_mov_b64_e32 v[106:107], 0
	v_mov_b64_e32 v[108:109], 0
	v_mov_b64_e32 v[110:111], 0
	v_mov_b64_e32 v[112:113], 0
	v_mov_b64_e32 v[114:115], 0
	v_mov_b64_e32 v[116:117], 0
	v_mov_b64_e32 v[118:119], 0
	v_mov_b64_e32 v[120:121], 0
	v_mov_b64_e32 v[122:123], 0
	v_mov_b64_e32 v[124:125], 0
	v_mov_b64_e32 v[126:127], 0

; #define PG8_WAIT_V(n) asm volatile("s_waitcnt vmcnt(" #n ")" ::: "memory")
;     ...
;         const bool has_next = S.next(ui + 1, nxt);
;         const char* nA = has_next ? (const char*)g.A + (size_t)nxt.pm * tA : cA; const char* nB = has_next ? (const char*)g.Bt + (size_t)nxt.pn * tB : cB;
; #pragma unroll 1
;         for (int t = 0; t < nt; t += 2) {
;             const bool last = (t == nt - 2);
;             const char* a1 = cA + (size_t)(t + 1) * kstep;
;             const char* a2 = last ? nA : cA + (size_t)(t + 2) * kstep; const char* b2 = last ? nB : cB + (size_t)(t + 2) * kstep;
;             const char* a3 = a2 + kstep; const char* b3 = b2 + kstep;
;             if (last && has_next) PG8_A_READY(nxt);
;             PG8_LDB(B0, 0, 0); PG8_SCHED; PG8_LDA(At, 0, 0); PG8_STAGE(PG8_SA(1, 1), a1 + hA, voffA);
;             PG8_WAIT_L(8); PG8_BAR; PG8_WAIT_L(0); PG8_MMA(0, 0, At, B0); PG8_BAR; PG8_SCHED;
;             PG8_LDB(B1, 0, 1); PG8_STAGE(PG8_SB(0, 0), b2, voffB);
;             PG8_BAR; PG8_WAIT_L(0); PG8_MMA(0, 1, At, B1); PG8_BAR;
;             PG8_LDA(At, 0, 1); PG8_STAGE(PG8_SA(0, 0), a2, voffA);
;             PG8_BAR; PG8_WAIT_L(0); PG8_MMA(1, 0, At, B0); PG8_BAR; PG8_SCHED;
;             PG8_STAGE(PG8_SB(0, 1), b2 + hB, voffB);
;             PG8_WAIT_V(6); PG8_BAR; PG8_MMA(1, 1, At, B1); PG8_BAR;
;             PG8_LDB(B0, 1, 0); PG8_SCHED; PG8_LDA(At, 1, 0); PG8_STAGE(PG8_SA(0, 1), a2 + hA, voffA);
;             PG8_WAIT_L(8); PG8_BAR; PG8_WAIT_L(0); PG8_MMA(0, 0, At, B0); PG8_BAR; PG8_SCHED;
;             PG8_LDB(B1, 1, 1); PG8_STAGE(PG8_SB(1, 0), b3, voffB);
;             PG8_BAR; PG8_WAIT_L(0); PG8_MMA(0, 1, At, B1); PG8_BAR;
;             PG8_LDA(At, 1, 1); PG8_STAGE(PG8_SA(1, 0), a3, voffA);
;             PG8_BAR; PG8_WAIT_L(0); PG8_MMA(1, 0, At, B0); PG8_BAR; PG8_SCHED;
;             PG8_STAGE(PG8_SB(1, 1), b3 + hB, voffB);
;             PG8_WAIT_V(6); PG8_BAR; PG8_MMA(1, 1, At, B1); PG8_BAR;
;         }
;         E(acc, cur, wr, wc, fr, fq);
;         if (!has_next) break;
; #pragma unroll
;         for (int a = 0; a < 2; ++a)
; #pragma unroll
;             for (int b = 0; b < 2; ++b)
; #pragma unroll
;                 for (int m = 0; m < 4; ++m)
; #pragma unroll
;                     for (int n = 0; n < 2; ++n) acc[a][b][m][n] = (f32x4){0.f, 0.f, 0.f, 0.f};
;         cur = nxt; cA = nA; cB = nB; ++ui;
.LBB0_1472:
	s_ashr_i32 s31, s30, 31
	s_lshl_b64 s[8:9], s[30:31], 17
	s_lshr_b32 s98, s28, 2
	s_lshl_b32 s98, s98, 8
	s_add_u32 s8, s8, s98
	v_cmp_lt_i64_e32 vcc, s[34:35], v[138:139]
	s_add_u32 s34, s12, s8
	s_addc_u32 s35, s13, s9
	s_and_b64 s[8:9], vcc, exec
	s_cselect_b32 s7, s35, s43
	s_cselect_b32 s8, s34, s42
	s_ashr_i32 s29, s28, 31
	s_lshl_b64 s[36:37], s[28:29], 17
	s_add_u32 s36, s36, s98
	s_add_u32 s36, s14, s36
	s_addc_u32 s37, s15, s37
	s_and_b64 s[44:45], vcc, exec
	v_mov_b32_e32 v0, 0
	s_cselect_b32 s9, s37, s41
	s_cselect_b32 s29, s36, s40
	s_mov_b64 s[58:59], 0
	s_mov_b64 s[54:55], 0
	s_mov_b64 s[56:57], -1
	v_mov_b32_e32 v1, v0
	v_mov_b64_e32 v[2:3], 0
	v_mov_b64_e32 v[4:5], 0
	v_mov_b64_e32 v[6:7], 0
	v_mov_b64_e32 v[8:9], 0
	v_mov_b64_e32 v[10:11], 0
	v_mov_b64_e32 v[12:13], 0
	v_mov_b64_e32 v[14:15], 0
	v_mov_b64_e32 v[16:17], 0
	v_mov_b64_e32 v[18:19], 0
	v_mov_b64_e32 v[20:21], 0
	v_mov_b64_e32 v[22:23], 0
	v_mov_b64_e32 v[24:25], 0
	v_mov_b64_e32 v[26:27], 0
	v_mov_b64_e32 v[28:29], 0
	v_mov_b64_e32 v[30:31], 0
	v_mov_b64_e32 v[32:33], 0
	v_mov_b64_e32 v[34:35], 0
	v_mov_b64_e32 v[36:37], 0
	v_mov_b64_e32 v[38:39], 0
	v_mov_b64_e32 v[40:41], 0
	v_mov_b64_e32 v[42:43], 0
	v_mov_b64_e32 v[44:45], 0
	v_mov_b64_e32 v[46:47], 0
	v_mov_b64_e32 v[48:49], 0
	v_mov_b64_e32 v[50:51], 0
	v_mov_b64_e32 v[52:53], 0
	v_mov_b64_e32 v[54:55], 0
	v_mov_b64_e32 v[56:57], 0
	v_mov_b64_e32 v[58:59], 0
	v_mov_b64_e32 v[60:61], 0
	v_mov_b64_e32 v[62:63], 0
	v_mov_b64_e32 v[64:65], 0
	v_mov_b64_e32 v[66:67], 0
	v_mov_b64_e32 v[68:69], 0
	v_mov_b64_e32 v[70:71], 0
	v_mov_b64_e32 v[72:73], 0
	v_mov_b64_e32 v[74:75], 0
	v_mov_b64_e32 v[76:77], 0
	v_mov_b64_e32 v[78:79], 0
	v_mov_b64_e32 v[80:81], 0
	v_mov_b64_e32 v[82:83], 0
	v_mov_b64_e32 v[84:85], 0
	v_mov_b64_e32 v[86:87], 0
	v_mov_b64_e32 v[88:89], 0
	v_mov_b64_e32 v[90:91], 0
	v_mov_b64_e32 v[92:93], 0
	v_mov_b64_e32 v[94:95], 0
	v_mov_b64_e32 v[96:97], 0
	v_mov_b64_e32 v[98:99], 0
	v_mov_b64_e32 v[100:101], 0
	v_mov_b64_e32 v[102:103], 0
	v_mov_b64_e32 v[104:105], 0
	v_mov_b64_e32 v[106:107], 0
	v_mov_b64_e32 v[108:109], 0
	v_mov_b64_e32 v[110:111], 0
	v_mov_b64_e32 v[112:113], 0
	v_mov_b64_e32 v[114:115], 0
	v_mov_b64_e32 v[116:117], 0
	v_mov_b64_e32 v[118:119], 0
	v_mov_b64_e32 v[120:121], 0
	v_mov_b64_e32 v[122:123], 0
	v_mov_b64_e32 v[124:125], 0
	v_mov_b64_e32 v[126:127], 0

; #define PG8_WAIT_V(n) asm volatile("s_waitcnt vmcnt(" #n ")" ::: "memory")
;     ...
;         const bool has_next = S.next(ui + 1, nxt);
;         const char* nA = has_next ? (const char*)g.A + (size_t)nxt.pm * tA : cA; const char* nB = has_next ? (const char*)g.Bt + (size_t)nxt.pn * tB : cB;
; #pragma unroll 1
;         for (int t = 0; t < nt; t += 2) {
;             const bool last = (t == nt - 2);
;             const char* a1 = cA + (size_t)(t + 1) * kstep;
;             const char* a2 = last ? nA : cA + (size_t)(t + 2) * kstep; const char* b2 = last ? nB : cB + (size_t)(t + 2) * kstep;
;             const char* a3 = a2 + kstep; const char* b3 = b2 + kstep;
;             if (last && has_next) PG8_A_READY(nxt);
;             PG8_LDB(B0, 0, 0); PG8_SCHED; PG8_LDA(At, 0, 0); PG8_STAGE(PG8_SA(1, 1), a1 + hA, voffA);
;             PG8_WAIT_L(8); PG8_BAR; PG8_WAIT_L(0); PG8_MMA(0, 0, At, B0); PG8_BAR; PG8_SCHED;
;             PG8_LDB(B1, 0, 1); PG8_STAGE(PG8_SB(0, 0), b2, voffB);
;             PG8_BAR; PG8_WAIT_L(0); PG8_MMA(0, 1, At, B1); PG8_BAR;
;             PG8_LDA(At, 0, 1); PG8_STAGE(PG8_SA(0, 0), a2, voffA);
;             PG8_BAR; PG8_WAIT_L(0); PG8_MMA(1, 0, At, B0); PG8_BAR; PG8_SCHED;
;             PG8_STAGE(PG8_SB(0, 1), b2 + hB, voffB);
;             PG8_WAIT_V(6); PG8_BAR; PG8_MMA(1, 1, At, B1); PG8_BAR;
;             PG8_LDB(B0, 1, 0); PG8_SCHED; PG8_LDA(At, 1, 0); PG8_STAGE(PG8_SA(0, 1), a2 + hA, voffA);
;             PG8_WAIT_L(8); PG8_BAR; PG8_WAIT_L(0); PG8_MMA(0, 0, At, B0); PG8_BAR; PG8_SCHED;
;             PG8_LDB(B1, 1, 1); PG8_STAGE(PG8_SB(1, 0), b3, voffB);
;             PG8_BAR; PG8_WAIT_L(0); PG8_MMA(0, 1, At, B1); PG8_BAR;
;             PG8_LDA(At, 1, 1); PG8_STAGE(PG8_SA(1, 0), a3, voffA);
;             PG8_BAR; PG8_WAIT_L(0); PG8_MMA(1, 0, At, B0); PG8_BAR; PG8_SCHED;
;             PG8_STAGE(PG8_SB(1, 1), b3 + hB, voffB);
;             PG8_WAIT_V(6); PG8_BAR; PG8_MMA(1, 1, At, B1); PG8_BAR;
;         }
;         E(acc, cur, wr, wc, fr, fq);
;         if (!has_next) break;
; #pragma unroll
;         for (int a = 0; a < 2; ++a)
; #pragma unroll
;             for (int b = 0; b < 2; ++b)
; #pragma unroll
;                 for (int m = 0; m < 4; ++m)
; #pragma unroll
;                     for (int n = 0; n < 2; ++n) acc[a][b][m][n] = (f32x4){0.f, 0.f, 0.f, 0.f};
;         cur = nxt; cA = nA; cB = nB; ++ui;
.LBB0_1484:
	s_ashr_i32 s25, s24, 31
	s_lshl_b64 s[8:9], s[24:25], 18
	s_lshl_b32 s98, s22, 9
	s_add_u32 s8, s8, s98
	v_cmp_lt_i64_e32 vcc, s[26:27], v[158:159]
	s_add_u32 s26, s12, s8
	s_addc_u32 s27, s13, s9
	s_and_b64 s[8:9], vcc, exec
	s_cselect_b32 s7, s27, s37
	s_cselect_b32 s8, s26, s36
	s_ashr_i32 s23, s22, 31
	s_lshl_b64 s[28:29], s[22:23], 18
	s_add_u32 s28, s28, s98
	s_add_u32 s28, s14, s28
	s_addc_u32 s29, s15, s29
	s_and_b64 s[38:39], vcc, exec
	s_cselect_b32 s9, s29, s35
	s_cselect_b32 s23, s28, s34
	s_add_u32 s25, s34, 0x100
	s_addc_u32 s33, s35, 0
	s_add_u32 s34, s36, 0x20080
	v_mov_b32_e32 v0, 0
	s_addc_u32 s35, s37, 0
	s_mov_b32 s44, -2
	v_mov_b32_e32 v1, v0
	v_mov_b64_e32 v[2:3], 0
	v_mov_b64_e32 v[4:5], 0
	v_mov_b64_e32 v[6:7], 0
	v_mov_b64_e32 v[8:9], 0
	v_mov_b64_e32 v[10:11], 0
	v_mov_b64_e32 v[12:13], 0
	v_mov_b64_e32 v[14:15], 0
	v_mov_b64_e32 v[16:17], 0
	v_mov_b64_e32 v[18:19], 0
	v_mov_b64_e32 v[20:21], 0
	v_mov_b64_e32 v[22:23], 0
	v_mov_b64_e32 v[24:25], 0
	v_mov_b64_e32 v[26:27], 0
	v_mov_b64_e32 v[28:29], 0
	v_mov_b64_e32 v[30:31], 0
	v_mov_b64_e32 v[32:33], 0
	v_mov_b64_e32 v[34:35], 0
	v_mov_b64_e32 v[36:37], 0
	v_mov_b64_e32 v[38:39], 0
	v_mov_b64_e32 v[40:41], 0
	v_mov_b64_e32 v[42:43], 0
	v_mov_b64_e32 v[44:45], 0
	v_mov_b64_e32 v[46:47], 0
	v_mov_b64_e32 v[48:49], 0
	v_mov_b64_e32 v[50:51], 0
	v_mov_b64_e32 v[52:53], 0
	v_mov_b64_e32 v[54:55], 0
	v_mov_b64_e32 v[56:57], 0
	v_mov_b64_e32 v[58:59], 0
	v_mov_b64_e32 v[60:61], 0
	v_mov_b64_e32 v[62:63], 0
	v_mov_b64_e32 v[64:65], 0
	v_mov_b64_e32 v[66:67], 0
	v_mov_b64_e32 v[68:69], 0
	v_mov_b64_e32 v[70:71], 0
	v_mov_b64_e32 v[72:73], 0
	v_mov_b64_e32 v[74:75], 0
	v_mov_b64_e32 v[76:77], 0
	v_mov_b64_e32 v[78:79], 0
	v_mov_b64_e32 v[80:81], 0
	v_mov_b64_e32 v[82:83], 0
	v_mov_b64_e32 v[84:85], 0
	v_mov_b64_e32 v[86:87], 0
	v_mov_b64_e32 v[88:89], 0
	v_mov_b64_e32 v[90:91], 0
	v_mov_b64_e32 v[92:93], 0
	v_mov_b64_e32 v[94:95], 0
	v_mov_b64_e32 v[96:97], 0
	v_mov_b64_e32 v[98:99], 0
	v_mov_b64_e32 v[100:101], 0
	v_mov_b64_e32 v[102:103], 0
	v_mov_b64_e32 v[104:105], 0
	v_mov_b64_e32 v[106:107], 0
	v_mov_b64_e32 v[108:109], 0
	v_mov_b64_e32 v[110:111], 0
	v_mov_b64_e32 v[112:113], 0
	v_mov_b64_e32 v[114:115], 0
	v_mov_b64_e32 v[116:117], 0
	v_mov_b64_e32 v[118:119], 0
	v_mov_b64_e32 v[120:121], 0
	v_mov_b64_e32 v[122:123], 0
	v_mov_b64_e32 v[124:125], 0
	v_mov_b64_e32 v[126:127], 0

; #define PG8_WAIT_V(n) asm volatile("s_waitcnt vmcnt(" #n ")" ::: "memory")
;     ...
;         const bool has_next = S.next(ui + 1, nxt);
;         const char* nA = has_next ? (const char*)g.A + (size_t)nxt.pm * tA : cA; const char* nB = has_next ? (const char*)g.Bt + (size_t)nxt.pn * tB : cB;
; #pragma unroll 1
;         for (int t = 0; t < nt; t += 2) {
;             const bool last = (t == nt - 2);
;             const char* a1 = cA + (size_t)(t + 1) * kstep;
;             const char* a2 = last ? nA : cA + (size_t)(t + 2) * kstep; const char* b2 = last ? nB : cB + (size_t)(t + 2) * kstep;
;             const char* a3 = a2 + kstep; const char* b3 = b2 + kstep;
;             if (last && has_next) PG8_A_READY(nxt);
;             PG8_LDB(B0, 0, 0); PG8_SCHED; PG8_LDA(At, 0, 0); PG8_STAGE(PG8_SA(1, 1), a1 + hA, voffA);
;             PG8_WAIT_L(8); PG8_BAR; PG8_WAIT_L(0); PG8_MMA(0, 0, At, B0); PG8_BAR; PG8_SCHED;
;             PG8_LDB(B1, 0, 1); PG8_STAGE(PG8_SB(0, 0), b2, voffB);
;             PG8_BAR; PG8_WAIT_L(0); PG8_MMA(0, 1, At, B1); PG8_BAR;
;             PG8_LDA(At, 0, 1); PG8_STAGE(PG8_SA(0, 0), a2, voffA);
;             PG8_BAR; PG8_WAIT_L(0); PG8_MMA(1, 0, At, B0); PG8_BAR; PG8_SCHED;
;             PG8_STAGE(PG8_SB(0, 1), b2 + hB, voffB);
;             PG8_WAIT_V(6); PG8_BAR; PG8_MMA(1, 1, At, B1); PG8_BAR;
;             PG8_LDB(B0, 1, 0); PG8_SCHED; PG8_LDA(At, 1, 0); PG8_STAGE(PG8_SA(0, 1), a2 + hA, voffA);
;             PG8_WAIT_L(8); PG8_BAR; PG8_WAIT_L(0); PG8_MMA(0, 0, At, B0); PG8_BAR; PG8_SCHED;
;             PG8_LDB(B1, 1, 1); PG8_STAGE(PG8_SB(1, 0), b3, voffB);
;             PG8_BAR; PG8_WAIT_L(0); PG8_MMA(0, 1, At, B1); PG8_BAR;
;             PG8_LDA(At, 1, 1); PG8_STAGE(PG8_SA(1, 0), a3, voffA);
;             PG8_BAR; PG8_WAIT_L(0); PG8_MMA(1, 0, At, B0); PG8_BAR; PG8_SCHED;
;             PG8_STAGE(PG8_SB(1, 1), b3 + hB, voffB);
;             PG8_WAIT_V(6); PG8_BAR; PG8_MMA(1, 1, At, B1); PG8_BAR;
;         }
;         E(acc, cur, wr, wc, fr, fq);
;         if (!has_next) break;
; #pragma unroll
;         for (int a = 0; a < 2; ++a)
; #pragma unroll
;             for (int b = 0; b < 2; ++b)
; #pragma unroll
;                 for (int m = 0; m < 4; ++m)
; #pragma unroll
;                     for (int n = 0; n < 2; ++n) acc[a][b][m][n] = (f32x4){0.f, 0.f, 0.f, 0.f};
;         cur = nxt; cA = nA; cB = nB; ++ui;
.LBB0_1767:
	s_ashr_i32 s27, s26, 31
	s_lshl_b64 s[16:17], s[26:27], 18
	s_add_u32 s30, s20, s16
	s_addc_u32 s31, s21, s17
	s_and_b64 s[10:11], s[10:11], exec
	s_cselect_b32 s27, s31, s15
	s_cselect_b32 s33, s30, s14
	s_add_u32 s44, s14, 0x100
	v_mov_b32_e32 v0, 0
	s_addc_u32 s45, s15, 0
	s_mov_b32 s60, -2
	v_mov_b32_e32 v1, v0
	v_mov_b64_e32 v[2:3], 0
	v_mov_b64_e32 v[4:5], 0
	v_mov_b64_e32 v[6:7], 0
	v_mov_b64_e32 v[8:9], 0
	v_mov_b64_e32 v[10:11], 0
	v_mov_b64_e32 v[12:13], 0
	v_mov_b64_e32 v[14:15], 0
	v_mov_b64_e32 v[16:17], 0
	v_mov_b64_e32 v[18:19], 0
	v_mov_b64_e32 v[20:21], 0
	v_mov_b64_e32 v[22:23], 0
	v_mov_b64_e32 v[24:25], 0
	v_mov_b64_e32 v[26:27], 0
	v_mov_b64_e32 v[28:29], 0
	v_mov_b64_e32 v[30:31], 0
	v_mov_b64_e32 v[32:33], 0
	v_mov_b64_e32 v[34:35], 0
	v_mov_b64_e32 v[36:37], 0
	v_mov_b64_e32 v[38:39], 0
	v_mov_b64_e32 v[40:41], 0
	v_mov_b64_e32 v[42:43], 0
	v_mov_b64_e32 v[44:45], 0
	v_mov_b64_e32 v[46:47], 0
	v_mov_b64_e32 v[48:49], 0
	v_mov_b64_e32 v[50:51], 0
	v_mov_b64_e32 v[52:53], 0
	v_mov_b64_e32 v[54:55], 0
	v_mov_b64_e32 v[56:57], 0
	v_mov_b64_e32 v[58:59], 0
	v_mov_b64_e32 v[60:61], 0
	v_mov_b64_e32 v[62:63], 0
	v_mov_b64_e32 v[64:65], 0
	v_mov_b64_e32 v[66:67], 0
	v_mov_b64_e32 v[68:69], 0
	v_mov_b64_e32 v[70:71], 0
	v_mov_b64_e32 v[72:73], 0
	v_mov_b64_e32 v[74:75], 0
	v_mov_b64_e32 v[76:77], 0
	v_mov_b64_e32 v[78:79], 0
	v_mov_b64_e32 v[80:81], 0
	v_mov_b64_e32 v[82:83], 0
	v_mov_b64_e32 v[84:85], 0
	v_mov_b64_e32 v[86:87], 0
	v_mov_b64_e32 v[88:89], 0
	v_mov_b64_e32 v[90:91], 0
	v_mov_b64_e32 v[92:93], 0
	v_mov_b64_e32 v[94:95], 0
	v_mov_b64_e32 v[96:97], 0
	v_mov_b64_e32 v[98:99], 0
	v_mov_b64_e32 v[100:101], 0
	v_mov_b64_e32 v[102:103], 0
	v_mov_b64_e32 v[104:105], 0
	v_mov_b64_e32 v[106:107], 0
	v_mov_b64_e32 v[108:109], 0
	v_mov_b64_e32 v[110:111], 0
	v_mov_b64_e32 v[112:113], 0
	v_mov_b64_e32 v[114:115], 0
	v_mov_b64_e32 v[116:117], 0
	v_mov_b64_e32 v[118:119], 0
	v_mov_b64_e32 v[120:121], 0
	v_mov_b64_e32 v[122:123], 0
	v_mov_b64_e32 v[124:125], 0
	v_mov_b64_e32 v[126:127], 0

; #define PG8_WAIT_V(n) asm volatile("s_waitcnt vmcnt(" #n ")" ::: "memory")
;     ...
;         const bool has_next = S.next(ui + 1, nxt);
;         const char* nA = has_next ? (const char*)g.A + (size_t)nxt.pm * tA : cA; const char* nB = has_next ? (const char*)g.Bt + (size_t)nxt.pn * tB : cB;
; #pragma unroll 1
;         for (int t = 0; t < nt; t += 2) {
;             const bool last = (t == nt - 2);
;             const char* a1 = cA + (size_t)(t + 1) * kstep;
;             const char* a2 = last ? nA : cA + (size_t)(t + 2) * kstep; const char* b2 = last ? nB : cB + (size_t)(t + 2) * kstep;
;             const char* a3 = a2 + kstep; const char* b3 = b2 + kstep;
;             if (last && has_next) PG8_A_READY(nxt);
;             PG8_LDB(B0, 0, 0); PG8_SCHED; PG8_LDA(At, 0, 0); PG8_STAGE(PG8_SA(1, 1), a1 + hA, voffA);
;             PG8_WAIT_L(8); PG8_BAR; PG8_WAIT_L(0); PG8_MMA(0, 0, At, B0); PG8_BAR; PG8_SCHED;
;             PG8_LDB(B1, 0, 1); PG8_STAGE(PG8_SB(0, 0), b2, voffB);
;             PG8_BAR; PG8_WAIT_L(0); PG8_MMA(0, 1, At, B1); PG8_BAR;
;             PG8_LDA(At, 0, 1); PG8_STAGE(PG8_SA(0, 0), a2, voffA);
;             PG8_BAR; PG8_WAIT_L(0); PG8_MMA(1, 0, At, B0); PG8_BAR; PG8_SCHED;
;             PG8_STAGE(PG8_SB(0, 1), b2 + hB, voffB);
;             PG8_WAIT_V(6); PG8_BAR; PG8_MMA(1, 1, At, B1); PG8_BAR;
;             PG8_LDB(B0, 1, 0); PG8_SCHED; PG8_LDA(At, 1, 0); PG8_STAGE(PG8_SA(0, 1), a2 + hA, voffA);
;             PG8_WAIT_L(8); PG8_BAR; PG8_WAIT_L(0); PG8_MMA(0, 0, At, B0); PG8_BAR; PG8_SCHED;
;             PG8_LDB(B1, 1, 1); PG8_STAGE(PG8_SB(1, 0), b3, voffB);
;             PG8_BAR; PG8_WAIT_L(0); PG8_MMA(0, 1, At, B1); PG8_BAR;
;             PG8_LDA(At, 1, 1); PG8_STAGE(PG8_SA(1, 0), a3, voffA);
;             PG8_BAR; PG8_WAIT_L(0); PG8_MMA(1, 0, At, B0); PG8_BAR; PG8_SCHED;
;             PG8_STAGE(PG8_SB(1, 1), b3 + hB, voffB);
;             PG8_WAIT_V(6); PG8_BAR; PG8_MMA(1, 1, At, B1); PG8_BAR;
;         }
;         E(acc, cur, wr, wc, fr, fq);
;         if (!has_next) break;
; #pragma unroll
;         for (int a = 0; a < 2; ++a)
; #pragma unroll
;             for (int b = 0; b < 2; ++b)
; #pragma unroll
;                 for (int m = 0; m < 4; ++m)
; #pragma unroll
;                     for (int n = 0; n < 2; ++n) acc[a][b][m][n] = (f32x4){0.f, 0.f, 0.f, 0.f};
;         cur = nxt; cA = nA; cB = nB; ++ui;
.LBB0_1840:
	s_ashr_i32 s39, s38, 31
	v_cmp_lt_i64_e32 vcc, s[16:17], v[140:141]
	s_lshl_b64 s[16:17], s[38:39], 18
	s_add_u32 s52, s58, s16
	s_addc_u32 s53, s59, s17
	s_and_b64 s[16:17], vcc, exec
	s_cselect_b32 s7, s53, s13
	s_cselect_b32 s18, s52, s12
	s_ashr_i32 s55, s54, 31
	s_lshl_b64 s[16:17], s[54:55], 18
	s_add_u32 s42, s34, s16
	s_addc_u32 s43, s35, s17
	s_and_b64 s[16:17], vcc, exec
	s_cselect_b32 s19, s43, s15
	s_cselect_b32 s33, s42, s14
	s_add_u32 s39, s14, 0x100
	s_addc_u32 s44, s15, 0
	s_add_u32 s12, s12, 0x20080
	v_mov_b32_e32 v0, 0
	s_addc_u32 s13, s13, 0
	s_mov_b32 s45, -2
	v_mov_b32_e32 v1, v0
	v_mov_b64_e32 v[2:3], 0
	v_mov_b64_e32 v[4:5], 0
	v_mov_b64_e32 v[6:7], 0
	v_mov_b64_e32 v[8:9], 0
	v_mov_b64_e32 v[10:11], 0
	v_mov_b64_e32 v[12:13], 0
	v_mov_b64_e32 v[14:15], 0
	v_mov_b64_e32 v[16:17], 0
	v_mov_b64_e32 v[18:19], 0
	v_mov_b64_e32 v[20:21], 0
	v_mov_b64_e32 v[22:23], 0
	v_mov_b64_e32 v[24:25], 0
	v_mov_b64_e32 v[26:27], 0
	v_mov_b64_e32 v[28:29], 0
	v_mov_b64_e32 v[30:31], 0
	v_mov_b64_e32 v[32:33], 0
	v_mov_b64_e32 v[34:35], 0
	v_mov_b64_e32 v[36:37], 0
	v_mov_b64_e32 v[38:39], 0
	v_mov_b64_e32 v[40:41], 0
	v_mov_b64_e32 v[42:43], 0
	v_mov_b64_e32 v[44:45], 0
	v_mov_b64_e32 v[46:47], 0
	v_mov_b64_e32 v[48:49], 0
	v_mov_b64_e32 v[50:51], 0
	v_mov_b64_e32 v[52:53], 0
	v_mov_b64_e32 v[54:55], 0
	v_mov_b64_e32 v[56:57], 0
	v_mov_b64_e32 v[58:59], 0
	v_mov_b64_e32 v[60:61], 0
	v_mov_b64_e32 v[62:63], 0
	v_mov_b64_e32 v[64:65], 0
	v_mov_b64_e32 v[66:67], 0
	v_mov_b64_e32 v[68:69], 0
	v_mov_b64_e32 v[70:71], 0
	v_mov_b64_e32 v[72:73], 0
	v_mov_b64_e32 v[74:75], 0
	v_mov_b64_e32 v[76:77], 0
	v_mov_b64_e32 v[78:79], 0
	v_mov_b64_e32 v[80:81], 0
	v_mov_b64_e32 v[82:83], 0
	v_mov_b64_e32 v[84:85], 0
	v_mov_b64_e32 v[86:87], 0
	v_mov_b64_e32 v[88:89], 0
	v_mov_b64_e32 v[90:91], 0
	v_mov_b64_e32 v[92:93], 0
	v_mov_b64_e32 v[94:95], 0
	v_mov_b64_e32 v[96:97], 0
	v_mov_b64_e32 v[98:99], 0
	v_mov_b64_e32 v[100:101], 0
	v_mov_b64_e32 v[102:103], 0
	v_mov_b64_e32 v[104:105], 0
	v_mov_b64_e32 v[106:107], 0
	v_mov_b64_e32 v[108:109], 0
	v_mov_b64_e32 v[110:111], 0
	v_mov_b64_e32 v[112:113], 0
	v_mov_b64_e32 v[114:115], 0
	v_mov_b64_e32 v[116:117], 0
	v_mov_b64_e32 v[118:119], 0
	v_mov_b64_e32 v[120:121], 0
	v_mov_b64_e32 v[122:123], 0
	v_mov_b64_e32 v[124:125], 0
	v_mov_b64_e32 v[126:127], 0

; #define PG8_WAIT_V(n) asm volatile("s_waitcnt vmcnt(" #n ")" ::: "memory")
;     ...
;         const bool has_next = S.next(ui + 1, nxt);
;         const char* nA = has_next ? (const char*)g.A + (size_t)nxt.pm * tA : cA; const char* nB = has_next ? (const char*)g.Bt + (size_t)nxt.pn * tB : cB;
; #pragma unroll 1
;         for (int t = 0; t < nt; t += 2) {
;             const bool last = (t == nt - 2);
;             const char* a1 = cA + (size_t)(t + 1) * kstep;
;             const char* a2 = last ? nA : cA + (size_t)(t + 2) * kstep; const char* b2 = last ? nB : cB + (size_t)(t + 2) * kstep;
;             const char* a3 = a2 + kstep; const char* b3 = b2 + kstep;
;             if (last && has_next) PG8_A_READY(nxt);
;             PG8_LDB(B0, 0, 0); PG8_SCHED; PG8_LDA(At, 0, 0); PG8_STAGE(PG8_SA(1, 1), a1 + hA, voffA);
;             PG8_WAIT_L(8); PG8_BAR; PG8_WAIT_L(0); PG8_MMA(0, 0, At, B0); PG8_BAR; PG8_SCHED;
;             PG8_LDB(B1, 0, 1); PG8_STAGE(PG8_SB(0, 0), b2, voffB);
;             PG8_BAR; PG8_WAIT_L(0); PG8_MMA(0, 1, At, B1); PG8_BAR;
;             PG8_LDA(At, 0, 1); PG8_STAGE(PG8_SA(0, 0), a2, voffA);
;             PG8_BAR; PG8_WAIT_L(0); PG8_MMA(1, 0, At, B0); PG8_BAR; PG8_SCHED;
;             PG8_STAGE(PG8_SB(0, 1), b2 + hB, voffB);
;             PG8_WAIT_V(6); PG8_BAR; PG8_MMA(1, 1, At, B1); PG8_BAR;
;             PG8_LDB(B0, 1, 0); PG8_SCHED; PG8_LDA(At, 1, 0); PG8_STAGE(PG8_SA(0, 1), a2 + hA, voffA);
;             PG8_WAIT_L(8); PG8_BAR; PG8_WAIT_L(0); PG8_MMA(0, 0, At, B0); PG8_BAR; PG8_SCHED;
;             PG8_LDB(B1, 1, 1); PG8_STAGE(PG8_SB(1, 0), b3, voffB);
;             PG8_BAR; PG8_WAIT_L(0); PG8_MMA(0, 1, At, B1); PG8_BAR;
;             PG8_LDA(At, 1, 1); PG8_STAGE(PG8_SA(1, 0), a3, voffA);
;             PG8_BAR; PG8_WAIT_L(0); PG8_MMA(1, 0, At, B0); PG8_BAR; PG8_SCHED;
;             PG8_STAGE(PG8_SB(1, 1), b3 + hB, voffB);
;             PG8_WAIT_V(6); PG8_BAR; PG8_MMA(1, 1, At, B1); PG8_BAR;
;         }
;         E(acc, cur, wr, wc, fr, fq);
;         if (!has_next) break;
; #pragma unroll
;         for (int a = 0; a < 2; ++a)
; #pragma unroll
;             for (int b = 0; b < 2; ++b)
; #pragma unroll
;                 for (int m = 0; m < 4; ++m)
; #pragma unroll
;                     for (int n = 0; n < 2; ++n) acc[a][b][m][n] = (f32x4){0.f, 0.f, 0.f, 0.f};
;         cur = nxt; cA = nA; cB = nB; ++ui;
.LBB0_1863:
	s_ashr_i32 s37, s36, 31
	s_lshl_b64 s[16:17], s[36:37], 18
	s_add_u32 s42, s58, s16
	v_cmp_lt_i64_e64 s[14:15], s[14:15], 16
	s_addc_u32 s43, s59, s17
	s_and_b64 s[16:17], s[14:15], exec
	s_cselect_b32 s7, s43, s11
	s_cselect_b32 s16, s42, s10
	s_ashr_i32 s53, s52, 31
	s_lshl_b64 s[40:41], s[52:53], 18
	s_add_u32 s40, s18, s40
	s_addc_u32 s41, s19, s41
	s_and_b64 s[14:15], s[14:15], exec
	s_cselect_b32 s17, s41, s13
	s_cselect_b32 s33, s40, s12
	s_add_u32 s37, s12, 0x100
	s_addc_u32 s44, s13, 0
	s_add_u32 s10, s10, 0x20080
	v_mov_b32_e32 v0, 0
	s_addc_u32 s11, s11, 0
	s_mov_b32 s45, -2
	v_mov_b32_e32 v1, v0
	v_mov_b64_e32 v[2:3], 0
	v_mov_b64_e32 v[4:5], 0
	v_mov_b64_e32 v[6:7], 0
	v_mov_b64_e32 v[8:9], 0
	v_mov_b64_e32 v[10:11], 0
	v_mov_b64_e32 v[12:13], 0
	v_mov_b64_e32 v[14:15], 0
	v_mov_b64_e32 v[16:17], 0
	v_mov_b64_e32 v[18:19], 0
	v_mov_b64_e32 v[20:21], 0
	v_mov_b64_e32 v[22:23], 0
	v_mov_b64_e32 v[24:25], 0
	v_mov_b64_e32 v[26:27], 0
	v_mov_b64_e32 v[28:29], 0
	v_mov_b64_e32 v[30:31], 0
	v_mov_b64_e32 v[32:33], 0
	v_mov_b64_e32 v[34:35], 0
	v_mov_b64_e32 v[36:37], 0
	v_mov_b64_e32 v[38:39], 0
	v_mov_b64_e32 v[40:41], 0
	v_mov_b64_e32 v[42:43], 0
	v_mov_b64_e32 v[44:45], 0
	v_mov_b64_e32 v[46:47], 0
	v_mov_b64_e32 v[48:49], 0
	v_mov_b64_e32 v[50:51], 0
	v_mov_b64_e32 v[52:53], 0
	v_mov_b64_e32 v[54:55], 0
	v_mov_b64_e32 v[56:57], 0
	v_mov_b64_e32 v[58:59], 0
	v_mov_b64_e32 v[60:61], 0
	v_mov_b64_e32 v[62:63], 0
	v_mov_b64_e32 v[64:65], 0
	v_mov_b64_e32 v[66:67], 0
	v_mov_b64_e32 v[68:69], 0
	v_mov_b64_e32 v[70:71], 0
	v_mov_b64_e32 v[72:73], 0
	v_mov_b64_e32 v[74:75], 0
	v_mov_b64_e32 v[76:77], 0
	v_mov_b64_e32 v[78:79], 0
	v_mov_b64_e32 v[80:81], 0
	v_mov_b64_e32 v[82:83], 0
	v_mov_b64_e32 v[84:85], 0
	v_mov_b64_e32 v[86:87], 0
	v_mov_b64_e32 v[88:89], 0
	v_mov_b64_e32 v[90:91], 0
	v_mov_b64_e32 v[92:93], 0
	v_mov_b64_e32 v[94:95], 0
	v_mov_b64_e32 v[96:97], 0
	v_mov_b64_e32 v[98:99], 0
	v_mov_b64_e32 v[100:101], 0
	v_mov_b64_e32 v[102:103], 0
	v_mov_b64_e32 v[104:105], 0
	v_mov_b64_e32 v[106:107], 0
	v_mov_b64_e32 v[108:109], 0
	v_mov_b64_e32 v[110:111], 0
	v_mov_b64_e32 v[112:113], 0
	v_mov_b64_e32 v[114:115], 0
	v_mov_b64_e32 v[116:117], 0
	v_mov_b64_e32 v[118:119], 0
	v_mov_b64_e32 v[120:121], 0
	v_mov_b64_e32 v[122:123], 0
	v_mov_b64_e32 v[124:125], 0
	v_mov_b64_e32 v[126:127], 0

; #define PG8_WAIT_V(n) asm volatile("s_waitcnt vmcnt(" #n ")" ::: "memory")
;     ...
;         const bool has_next = S.next(ui + 1, nxt);
;         const char* nA = has_next ? (const char*)g.A + (size_t)nxt.pm * tA : cA; const char* nB = has_next ? (const char*)g.Bt + (size_t)nxt.pn * tB : cB;
; #pragma unroll 1
;         for (int t = 0; t < nt; t += 2) {
;             const bool last = (t == nt - 2);
;             const char* a1 = cA + (size_t)(t + 1) * kstep;
;             const char* a2 = last ? nA : cA + (size_t)(t + 2) * kstep; const char* b2 = last ? nB : cB + (size_t)(t + 2) * kstep;
;             const char* a3 = a2 + kstep; const char* b3 = b2 + kstep;
;             if (last && has_next) PG8_A_READY(nxt);
;             PG8_LDB(B0, 0, 0); PG8_SCHED; PG8_LDA(At, 0, 0); PG8_STAGE(PG8_SA(1, 1), a1 + hA, voffA);
;             PG8_WAIT_L(8); PG8_BAR; PG8_WAIT_L(0); PG8_MMA(0, 0, At, B0); PG8_BAR; PG8_SCHED;
;             PG8_LDB(B1, 0, 1); PG8_STAGE(PG8_SB(0, 0), b2, voffB);
;             PG8_BAR; PG8_WAIT_L(0); PG8_MMA(0, 1, At, B1); PG8_BAR;
;             PG8_LDA(At, 0, 1); PG8_STAGE(PG8_SA(0, 0), a2, voffA);
;             PG8_BAR; PG8_WAIT_L(0); PG8_MMA(1, 0, At, B0); PG8_BAR; PG8_SCHED;
;             PG8_STAGE(PG8_SB(0, 1), b2 + hB, voffB);
;             PG8_WAIT_V(6); PG8_BAR; PG8_MMA(1, 1, At, B1); PG8_BAR;
;             PG8_LDB(B0, 1, 0); PG8_SCHED; PG8_LDA(At, 1, 0); PG8_STAGE(PG8_SA(0, 1), a2 + hA, voffA);
;             PG8_WAIT_L(8); PG8_BAR; PG8_WAIT_L(0); PG8_MMA(0, 0, At, B0); PG8_BAR; PG8_SCHED;
;             PG8_LDB(B1, 1, 1); PG8_STAGE(PG8_SB(1, 0), b3, voffB);
;             PG8_BAR; PG8_WAIT_L(0); PG8_MMA(0, 1, At, B1); PG8_BAR;
;             PG8_LDA(At, 1, 1); PG8_STAGE(PG8_SA(1, 0), a3, voffA);
;             PG8_BAR; PG8_WAIT_L(0); PG8_MMA(1, 0, At, B0); PG8_BAR; PG8_SCHED;
;             PG8_STAGE(PG8_SB(1, 1), b3 + hB, voffB);
;             PG8_WAIT_V(6); PG8_BAR; PG8_MMA(1, 1, At, B1); PG8_BAR;
;         }
;         E(acc, cur, wr, wc, fr, fq);
;         if (!has_next) break;
; #pragma unroll
;         for (int a = 0; a < 2; ++a)
; #pragma unroll
;             for (int b = 0; b < 2; ++b)
; #pragma unroll
;                 for (int m = 0; m < 4; ++m)
; #pragma unroll
;                     for (int n = 0; n < 2; ++n) acc[a][b][m][n] = (f32x4){0.f, 0.f, 0.f, 0.f};
;         cur = nxt; cA = nA; cB = nB; ++ui;
.LBB0_1904:
	s_ashr_i32 s29, s28, 31
	s_lshl_b64 s[6:7], s[28:29], 19
	s_add_u32 s38, s18, s6
	s_addc_u32 s39, s19, s7
	s_and_b64 s[6:7], s[14:15], exec
	s_cselect_b32 s6, s39, s53
	s_cselect_b32 s7, s38, s52
	s_add_u32 s29, s42, 0x110000
	v_mov_b32_e32 v0, 0
	s_addc_u32 s33, s43, 0
	s_mov_b32 s41, 0
	s_waitcnt lgkmcnt(0)
	v_mov_b32_e32 v1, v0
	v_mov_b64_e32 v[2:3], 0
	v_mov_b64_e32 v[4:5], 0
	v_mov_b64_e32 v[6:7], 0
	v_mov_b64_e32 v[8:9], 0
	v_mov_b64_e32 v[10:11], 0
	v_mov_b64_e32 v[12:13], 0
	v_mov_b64_e32 v[14:15], 0
	v_mov_b64_e32 v[16:17], 0
	v_mov_b64_e32 v[18:19], 0
	v_mov_b64_e32 v[20:21], 0
	v_mov_b64_e32 v[22:23], 0
	v_mov_b64_e32 v[24:25], 0
	v_mov_b64_e32 v[26:27], 0
	v_mov_b64_e32 v[28:29], 0
	v_mov_b64_e32 v[30:31], 0
	v_mov_b64_e32 v[32:33], 0
	v_mov_b64_e32 v[34:35], 0
	v_mov_b64_e32 v[36:37], 0
	v_mov_b64_e32 v[38:39], 0
	v_mov_b64_e32 v[40:41], 0
	v_mov_b64_e32 v[42:43], 0
	v_mov_b64_e32 v[44:45], 0
	v_mov_b64_e32 v[46:47], 0
	v_mov_b64_e32 v[48:49], 0
	v_mov_b64_e32 v[50:51], 0
	v_mov_b64_e32 v[52:53], 0
	v_mov_b64_e32 v[54:55], 0
	v_mov_b64_e32 v[56:57], 0
	v_mov_b64_e32 v[58:59], 0
	v_mov_b64_e32 v[60:61], 0
	v_mov_b64_e32 v[62:63], 0
	v_mov_b64_e32 v[64:65], 0
	v_mov_b64_e32 v[66:67], 0
	v_mov_b64_e32 v[68:69], 0
	v_mov_b64_e32 v[70:71], 0
	v_mov_b64_e32 v[72:73], 0
	v_mov_b64_e32 v[74:75], 0
	v_mov_b64_e32 v[76:77], 0
	v_mov_b64_e32 v[78:79], 0
	v_mov_b64_e32 v[80:81], 0
	v_mov_b64_e32 v[82:83], 0
	v_mov_b64_e32 v[84:85], 0
	v_mov_b64_e32 v[86:87], 0
	v_mov_b64_e32 v[88:89], 0
	v_mov_b64_e32 v[90:91], 0
	v_mov_b64_e32 v[92:93], 0
	v_mov_b64_e32 v[94:95], 0
	v_mov_b64_e32 v[96:97], 0
	v_mov_b64_e32 v[98:99], 0
	v_mov_b64_e32 v[100:101], 0
	v_mov_b64_e32 v[102:103], 0
	v_mov_b64_e32 v[104:105], 0
	v_mov_b64_e32 v[106:107], 0
	v_mov_b64_e32 v[108:109], 0
	v_mov_b64_e32 v[110:111], 0
	v_mov_b64_e32 v[112:113], 0
	v_mov_b64_e32 v[114:115], 0
	v_mov_b64_e32 v[116:117], 0
	v_mov_b64_e32 v[118:119], 0
	v_mov_b64_e32 v[120:121], 0
	v_mov_b64_e32 v[122:123], 0
	v_mov_b64_e32 v[124:125], 0
	v_mov_b64_e32 v[126:127], 0
	s_branch .LBB0_1908

; #define PG8_WAIT_V(n) asm volatile("s_waitcnt vmcnt(" #n ")" ::: "memory")
;     ...
;         const bool has_next = S.next(ui + 1, nxt);
;         const char* nA = has_next ? (const char*)g.A + (size_t)nxt.pm * tA : cA; const char* nB = has_next ? (const char*)g.Bt + (size_t)nxt.pn * tB : cB;
; #pragma unroll 1
;         for (int t = 0; t < nt; t += 2) {
;             const bool last = (t == nt - 2);
;             const char* a1 = cA + (size_t)(t + 1) * kstep;
;             const char* a2 = last ? nA : cA + (size_t)(t + 2) * kstep; const char* b2 = last ? nB : cB + (size_t)(t + 2) * kstep;
;             const char* a3 = a2 + kstep; const char* b3 = b2 + kstep;
;             if (last && has_next) PG8_A_READY(nxt);
;             PG8_LDB(B0, 0, 0); PG8_SCHED; PG8_LDA(At, 0, 0); PG8_STAGE(PG8_SA(1, 1), a1 + hA, voffA);
;             PG8_WAIT_L(8); PG8_BAR; PG8_WAIT_L(0); PG8_MMA(0, 0, At, B0); PG8_BAR; PG8_SCHED;
;             PG8_LDB(B1, 0, 1); PG8_STAGE(PG8_SB(0, 0), b2, voffB);
;             PG8_BAR; PG8_WAIT_L(0); PG8_MMA(0, 1, At, B1); PG8_BAR;
;             PG8_LDA(At, 0, 1); PG8_STAGE(PG8_SA(0, 0), a2, voffA);
;             PG8_BAR; PG8_WAIT_L(0); PG8_MMA(1, 0, At, B0); PG8_BAR; PG8_SCHED;
;             PG8_STAGE(PG8_SB(0, 1), b2 + hB, voffB);
;             PG8_WAIT_V(6); PG8_BAR; PG8_MMA(1, 1, At, B1); PG8_BAR;
;             PG8_LDB(B0, 1, 0); PG8_SCHED; PG8_LDA(At, 1, 0); PG8_STAGE(PG8_SA(0, 1), a2 + hA, voffA);
;             PG8_WAIT_L(8); PG8_BAR; PG8_WAIT_L(0); PG8_MMA(0, 0, At, B0); PG8_BAR; PG8_SCHED;
;             PG8_LDB(B1, 1, 1); PG8_STAGE(PG8_SB(1, 0), b3, voffB);
;             PG8_BAR; PG8_WAIT_L(0); PG8_MMA(0, 1, At, B1); PG8_BAR;
;             PG8_LDA(At, 1, 1); PG8_STAGE(PG8_SA(1, 0), a3, voffA);
;             PG8_BAR; PG8_WAIT_L(0); PG8_MMA(1, 0, At, B0); PG8_BAR; PG8_SCHED;
;             PG8_STAGE(PG8_SB(1, 1), b3 + hB, voffB);
;             PG8_WAIT_V(6); PG8_BAR; PG8_MMA(1, 1, At, B1); PG8_BAR;
;         }
;         E(acc, cur, wr, wc, fr, fq);
;         if (!has_next) break;
; #pragma unroll
;         for (int a = 0; a < 2; ++a)
; #pragma unroll
;             for (int b = 0; b < 2; ++b)
; #pragma unroll
;                 for (int m = 0; m < 4; ++m)
; #pragma unroll
;                     for (int n = 0; n < 2; ++n) acc[a][b][m][n] = (f32x4){0.f, 0.f, 0.f, 0.f};
;         cur = nxt; cA = nA; cB = nB; ++ui;
.LBB0_1977:
	s_ashr_i32 s43, s42, 31
	s_lshl_b64 s[56:57], s[42:43], 19
	s_add_u32 s56, s88, s56
	s_addc_u32 s57, s89, s57
	s_and_b64 s[58:59], s[52:53], exec
	v_mov_b32_e32 v0, 0
	s_cselect_b32 s43, s57, s37
	s_cselect_b32 s93, s56, s36
	s_mov_b32 s78, 0
	s_mov_b64 s[62:63], -1
	s_mov_b64 s[58:59], 0
	v_mov_b32_e32 v1, v0
	v_mov_b64_e32 v[2:3], 0
	v_mov_b64_e32 v[4:5], 0
	v_mov_b64_e32 v[6:7], 0
	v_mov_b64_e32 v[8:9], 0
	v_mov_b64_e32 v[10:11], 0
	v_mov_b64_e32 v[12:13], 0
	v_mov_b64_e32 v[14:15], 0
	v_mov_b64_e32 v[16:17], 0
	v_mov_b64_e32 v[18:19], 0
	v_mov_b64_e32 v[20:21], 0
	v_mov_b64_e32 v[22:23], 0
	v_mov_b64_e32 v[24:25], 0
	v_mov_b64_e32 v[26:27], 0
	v_mov_b64_e32 v[28:29], 0
	v_mov_b64_e32 v[30:31], 0
	v_mov_b64_e32 v[32:33], 0
	v_mov_b64_e32 v[34:35], 0
	v_mov_b64_e32 v[36:37], 0
	v_mov_b64_e32 v[38:39], 0
	v_mov_b64_e32 v[40:41], 0
	v_mov_b64_e32 v[42:43], 0
	v_mov_b64_e32 v[44:45], 0
	v_mov_b64_e32 v[46:47], 0
	v_mov_b64_e32 v[48:49], 0
	v_mov_b64_e32 v[50:51], 0
	v_mov_b64_e32 v[52:53], 0
	v_mov_b64_e32 v[54:55], 0
	v_mov_b64_e32 v[56:57], 0
	v_mov_b64_e32 v[58:59], 0
	v_mov_b64_e32 v[60:61], 0
	v_mov_b64_e32 v[62:63], 0
	v_mov_b64_e32 v[64:65], 0
	v_mov_b64_e32 v[66:67], 0
	v_mov_b64_e32 v[68:69], 0
	v_mov_b64_e32 v[70:71], 0
	v_mov_b64_e32 v[72:73], 0
	v_mov_b64_e32 v[74:75], 0
	v_mov_b64_e32 v[76:77], 0
	v_mov_b64_e32 v[78:79], 0
	v_mov_b64_e32 v[80:81], 0
	v_mov_b64_e32 v[82:83], 0
	v_mov_b64_e32 v[84:85], 0
	v_mov_b64_e32 v[86:87], 0
	v_mov_b64_e32 v[88:89], 0
	v_mov_b64_e32 v[90:91], 0
	v_mov_b64_e32 v[92:93], 0
	v_mov_b64_e32 v[94:95], 0
	v_mov_b64_e32 v[96:97], 0
	v_mov_b64_e32 v[98:99], 0
	v_mov_b64_e32 v[100:101], 0
	v_mov_b64_e32 v[102:103], 0
	v_mov_b64_e32 v[104:105], 0
	v_mov_b64_e32 v[106:107], 0
	v_mov_b64_e32 v[108:109], 0
	v_mov_b64_e32 v[110:111], 0
	v_mov_b64_e32 v[112:113], 0
	v_mov_b64_e32 v[114:115], 0
	v_mov_b64_e32 v[116:117], 0
	v_mov_b64_e32 v[118:119], 0
	v_mov_b64_e32 v[120:121], 0
	v_mov_b64_e32 v[122:123], 0
	v_mov_b64_e32 v[124:125], 0
	v_mov_b64_e32 v[126:127], 0
	s_branch .LBB0_1981

; #define PG8_WAIT_V(n) asm volatile("s_waitcnt vmcnt(" #n ")" ::: "memory")
;     ...
;         const bool has_next = S.next(ui + 1, nxt);
;         const char* nA = has_next ? (const char*)g.A + (size_t)nxt.pm * tA : cA; const char* nB = has_next ? (const char*)g.Bt + (size_t)nxt.pn * tB : cB;
; #pragma unroll 1
;         for (int t = 0; t < nt; t += 2) {
;             const bool last = (t == nt - 2);
;             const char* a1 = cA + (size_t)(t + 1) * kstep;
;             const char* a2 = last ? nA : cA + (size_t)(t + 2) * kstep; const char* b2 = last ? nB : cB + (size_t)(t + 2) * kstep;
;             const char* a3 = a2 + kstep; const char* b3 = b2 + kstep;
;             if (last && has_next) PG8_A_READY(nxt);
;             PG8_LDB(B0, 0, 0); PG8_SCHED; PG8_LDA(At, 0, 0); PG8_STAGE(PG8_SA(1, 1), a1 + hA, voffA);
;             PG8_WAIT_L(8); PG8_BAR; PG8_WAIT_L(0); PG8_MMA(0, 0, At, B0); PG8_BAR; PG8_SCHED;
;             PG8_LDB(B1, 0, 1); PG8_STAGE(PG8_SB(0, 0), b2, voffB);
;             PG8_BAR; PG8_WAIT_L(0); PG8_MMA(0, 1, At, B1); PG8_BAR;
;             PG8_LDA(At, 0, 1); PG8_STAGE(PG8_SA(0, 0), a2, voffA);
;             PG8_BAR; PG8_WAIT_L(0); PG8_MMA(1, 0, At, B0); PG8_BAR; PG8_SCHED;
;             PG8_STAGE(PG8_SB(0, 1), b2 + hB, voffB);
;             PG8_WAIT_V(6); PG8_BAR; PG8_MMA(1, 1, At, B1); PG8_BAR;
;             PG8_LDB(B0, 1, 0); PG8_SCHED; PG8_LDA(At, 1, 0); PG8_STAGE(PG8_SA(0, 1), a2 + hA, voffA);
;             PG8_WAIT_L(8); PG8_BAR; PG8_WAIT_L(0); PG8_MMA(0, 0, At, B0); PG8_BAR; PG8_SCHED;
;             PG8_LDB(B1, 1, 1); PG8_STAGE(PG8_SB(1, 0), b3, voffB);
;             PG8_BAR; PG8_WAIT_L(0); PG8_MMA(0, 1, At, B1); PG8_BAR;
;             PG8_LDA(At, 1, 1); PG8_STAGE(PG8_SA(1, 0), a3, voffA);
;             PG8_BAR; PG8_WAIT_L(0); PG8_MMA(1, 0, At, B0); PG8_BAR; PG8_SCHED;
;             PG8_STAGE(PG8_SB(1, 1), b3 + hB, voffB);
;             PG8_WAIT_V(6); PG8_BAR; PG8_MMA(1, 1, At, B1); PG8_BAR;
;         }
;         E(acc, cur, wr, wc, fr, fq);
;         if (!has_next) break;
; #pragma unroll
;         for (int a = 0; a < 2; ++a)
; #pragma unroll
;             for (int b = 0; b < 2; ++b)
; #pragma unroll
;                 for (int m = 0; m < 4; ++m)
; #pragma unroll
;                     for (int n = 0; n < 2; ++n) acc[a][b][m][n] = (f32x4){0.f, 0.f, 0.f, 0.f};
;         cur = nxt; cA = nA; cB = nB; ++ui;
.LBB0_2098:
	s_ashr_i32 s25, s24, 31
	v_cmp_lt_i64_e32 vcc, s[28:29], v[140:141]
	s_lshl_b64 s[28:29], s[24:25], 19
	s_add_u32 s30, s10, s28
	s_addc_u32 s31, s11, s29
	s_and_b64 s[28:29], vcc, exec
	s_cselect_b32 s25, s31, s37
	s_cselect_b32 s44, s30, s36
	s_ashr_i32 s35, s34, 31
	s_lshl_b64 s[28:29], s[34:35], 19
	s_add_u32 s28, s20, s28
	s_addc_u32 s29, s21, s29
	s_and_b64 s[40:41], vcc, exec
	s_cselect_b32 s35, s29, s39
	s_cselect_b32 s45, s28, s38
	s_add_u32 s69, s38, 0x100
	s_addc_u32 s70, s39, 0
	s_add_u32 s36, s36, 0x40080
	v_mov_b32_e32 v0, 0
	s_addc_u32 s37, s37, 0
	s_mov_b32 s71, -2
	v_mov_b32_e32 v1, v0
	v_mov_b64_e32 v[2:3], 0
	v_mov_b64_e32 v[4:5], 0
	v_mov_b64_e32 v[6:7], 0
	v_mov_b64_e32 v[8:9], 0
	v_mov_b64_e32 v[10:11], 0
	v_mov_b64_e32 v[12:13], 0
	v_mov_b64_e32 v[14:15], 0
	v_mov_b64_e32 v[16:17], 0
	v_mov_b64_e32 v[18:19], 0
	v_mov_b64_e32 v[20:21], 0
	v_mov_b64_e32 v[22:23], 0
	v_mov_b64_e32 v[24:25], 0
	v_mov_b64_e32 v[26:27], 0
	v_mov_b64_e32 v[28:29], 0
	v_mov_b64_e32 v[30:31], 0
	v_mov_b64_e32 v[32:33], 0
	v_mov_b64_e32 v[34:35], 0
	v_mov_b64_e32 v[36:37], 0
	v_mov_b64_e32 v[38:39], 0
	v_mov_b64_e32 v[40:41], 0
	v_mov_b64_e32 v[42:43], 0
	v_mov_b64_e32 v[44:45], 0
	v_mov_b64_e32 v[46:47], 0
	v_mov_b64_e32 v[48:49], 0
	v_mov_b64_e32 v[50:51], 0
	v_mov_b64_e32 v[52:53], 0
	v_mov_b64_e32 v[54:55], 0
	v_mov_b64_e32 v[56:57], 0
	v_mov_b64_e32 v[58:59], 0
	v_mov_b64_e32 v[60:61], 0
	v_mov_b64_e32 v[62:63], 0
	v_mov_b64_e32 v[64:65], 0
	v_mov_b64_e32 v[66:67], 0
	v_mov_b64_e32 v[68:69], 0
	v_mov_b64_e32 v[70:71], 0
	v_mov_b64_e32 v[72:73], 0
	v_mov_b64_e32 v[74:75], 0
	v_mov_b64_e32 v[76:77], 0
	v_mov_b64_e32 v[78:79], 0
	v_mov_b64_e32 v[80:81], 0
	v_mov_b64_e32 v[82:83], 0
	v_mov_b64_e32 v[84:85], 0
	v_mov_b64_e32 v[86:87], 0
	v_mov_b64_e32 v[88:89], 0
	v_mov_b64_e32 v[90:91], 0
	v_mov_b64_e32 v[92:93], 0
	v_mov_b64_e32 v[94:95], 0
	v_mov_b64_e32 v[96:97], 0
	v_mov_b64_e32 v[98:99], 0
	v_mov_b64_e32 v[100:101], 0
	v_mov_b64_e32 v[102:103], 0
	v_mov_b64_e32 v[104:105], 0
	v_mov_b64_e32 v[106:107], 0
	v_mov_b64_e32 v[108:109], 0
	v_mov_b64_e32 v[110:111], 0
	v_mov_b64_e32 v[112:113], 0
	v_mov_b64_e32 v[114:115], 0
	v_mov_b64_e32 v[116:117], 0
	v_mov_b64_e32 v[118:119], 0
	v_mov_b64_e32 v[120:121], 0
	v_mov_b64_e32 v[122:123], 0
	v_mov_b64_e32 v[124:125], 0
	v_mov_b64_e32 v[126:127], 0

; #define PG8_WAIT_V(n) asm volatile("s_waitcnt vmcnt(" #n ")" ::: "memory")
;     ...
;         const bool has_next = S.next(ui + 1, nxt);
;         const char* nA = has_next ? (const char*)g.A + (size_t)nxt.pm * tA : cA; const char* nB = has_next ? (const char*)g.Bt + (size_t)nxt.pn * tB : cB;
; #pragma unroll 1
;         for (int t = 0; t < nt; t += 2) {
;             const bool last = (t == nt - 2);
;             const char* a1 = cA + (size_t)(t + 1) * kstep;
;             const char* a2 = last ? nA : cA + (size_t)(t + 2) * kstep; const char* b2 = last ? nB : cB + (size_t)(t + 2) * kstep;
;             const char* a3 = a2 + kstep; const char* b3 = b2 + kstep;
;             if (last && has_next) PG8_A_READY(nxt);
;             PG8_LDB(B0, 0, 0); PG8_SCHED; PG8_LDA(At, 0, 0); PG8_STAGE(PG8_SA(1, 1), a1 + hA, voffA);
;             PG8_WAIT_L(8); PG8_BAR; PG8_WAIT_L(0); PG8_MMA(0, 0, At, B0); PG8_BAR; PG8_SCHED;
;             PG8_LDB(B1, 0, 1); PG8_STAGE(PG8_SB(0, 0), b2, voffB);
;             PG8_BAR; PG8_WAIT_L(0); PG8_MMA(0, 1, At, B1); PG8_BAR;
;             PG8_LDA(At, 0, 1); PG8_STAGE(PG8_SA(0, 0), a2, voffA);
;             PG8_BAR; PG8_WAIT_L(0); PG8_MMA(1, 0, At, B0); PG8_BAR; PG8_SCHED;
;             PG8_STAGE(PG8_SB(0, 1), b2 + hB, voffB);
;             PG8_WAIT_V(6); PG8_BAR; PG8_MMA(1, 1, At, B1); PG8_BAR;
;             PG8_LDB(B0, 1, 0); PG8_SCHED; PG8_LDA(At, 1, 0); PG8_STAGE(PG8_SA(0, 1), a2 + hA, voffA);
;             PG8_WAIT_L(8); PG8_BAR; PG8_WAIT_L(0); PG8_MMA(0, 0, At, B0); PG8_BAR; PG8_SCHED;
;             PG8_LDB(B1, 1, 1); PG8_STAGE(PG8_SB(1, 0), b3, voffB);
;             PG8_BAR; PG8_WAIT_L(0); PG8_MMA(0, 1, At, B1); PG8_BAR;
;             PG8_LDA(At, 1, 1); PG8_STAGE(PG8_SA(1, 0), a3, voffA);
;             PG8_BAR; PG8_WAIT_L(0); PG8_MMA(1, 0, At, B0); PG8_BAR; PG8_SCHED;
;             PG8_STAGE(PG8_SB(1, 1), b3 + hB, voffB);
;             PG8_WAIT_V(6); PG8_BAR; PG8_MMA(1, 1, At, B1); PG8_BAR;
;         }
;         E(acc, cur, wr, wc, fr, fq);
;         if (!has_next) break;
; #pragma unroll
;         for (int a = 0; a < 2; ++a)
; #pragma unroll
;             for (int b = 0; b < 2; ++b)
; #pragma unroll
;                 for (int m = 0; m < 4; ++m)
; #pragma unroll
;                     for (int n = 0; n < 2; ++n) acc[a][b][m][n] = (f32x4){0.f, 0.f, 0.f, 0.f};
;         cur = nxt; cA = nA; cB = nB; ++ui;
.LBB0_2121:
	s_ashr_i32 s21, s20, 31
	v_cmp_lt_i64_e64 s[38:39], s[24:25], 64
	s_lshl_b64 s[24:25], s[20:21], 19
	s_add_u32 s26, s42, s24
	s_addc_u32 s27, s43, s25
	s_and_b64 s[24:25], s[38:39], exec
	s_cselect_b32 s21, s27, s35
	s_cselect_b32 s44, s26, s34
	s_ashr_i32 s29, s28, 31
	s_lshl_b64 s[24:25], s[28:29], 19
	s_add_u32 s24, s12, s24
	s_addc_u32 s25, s13, s25
	s_and_b64 s[38:39], s[38:39], exec
	s_cselect_b32 s29, s25, s37
	s_cselect_b32 s45, s24, s36
	s_add_u32 s69, s36, 0x100
	s_addc_u32 s70, s37, 0
	s_add_u32 s34, s34, 0x40080
	v_mov_b32_e32 v0, 0
	s_addc_u32 s35, s35, 0
	s_mov_b32 s71, -2
	v_mov_b32_e32 v1, v0
	v_mov_b64_e32 v[2:3], 0
	v_mov_b64_e32 v[4:5], 0
	v_mov_b64_e32 v[6:7], 0
	v_mov_b64_e32 v[8:9], 0
	v_mov_b64_e32 v[10:11], 0
	v_mov_b64_e32 v[12:13], 0
	v_mov_b64_e32 v[14:15], 0
	v_mov_b64_e32 v[16:17], 0
	v_mov_b64_e32 v[18:19], 0
	v_mov_b64_e32 v[20:21], 0
	v_mov_b64_e32 v[22:23], 0
	v_mov_b64_e32 v[24:25], 0
	v_mov_b64_e32 v[26:27], 0
	v_mov_b64_e32 v[28:29], 0
	v_mov_b64_e32 v[30:31], 0
	v_mov_b64_e32 v[32:33], 0
	v_mov_b64_e32 v[34:35], 0
	v_mov_b64_e32 v[36:37], 0
	v_mov_b64_e32 v[38:39], 0
	v_mov_b64_e32 v[40:41], 0
	v_mov_b64_e32 v[42:43], 0
	v_mov_b64_e32 v[44:45], 0
	v_mov_b64_e32 v[46:47], 0
	v_mov_b64_e32 v[48:49], 0
	v_mov_b64_e32 v[50:51], 0
	v_mov_b64_e32 v[52:53], 0
	v_mov_b64_e32 v[54:55], 0
	v_mov_b64_e32 v[56:57], 0
	v_mov_b64_e32 v[58:59], 0
	v_mov_b64_e32 v[60:61], 0
	v_mov_b64_e32 v[62:63], 0
	v_mov_b64_e32 v[64:65], 0
	v_mov_b64_e32 v[66:67], 0
	v_mov_b64_e32 v[68:69], 0
	v_mov_b64_e32 v[70:71], 0
	v_mov_b64_e32 v[72:73], 0
	v_mov_b64_e32 v[74:75], 0
	v_mov_b64_e32 v[76:77], 0
	v_mov_b64_e32 v[78:79], 0
	v_mov_b64_e32 v[80:81], 0
	v_mov_b64_e32 v[82:83], 0
	v_mov_b64_e32 v[84:85], 0
	v_mov_b64_e32 v[86:87], 0
	v_mov_b64_e32 v[88:89], 0
	v_mov_b64_e32 v[90:91], 0
	v_mov_b64_e32 v[92:93], 0
	v_mov_b64_e32 v[94:95], 0
	v_mov_b64_e32 v[96:97], 0
	v_mov_b64_e32 v[98:99], 0
	v_mov_b64_e32 v[100:101], 0
	v_mov_b64_e32 v[102:103], 0
	v_mov_b64_e32 v[104:105], 0
	v_mov_b64_e32 v[106:107], 0
	v_mov_b64_e32 v[108:109], 0
	v_mov_b64_e32 v[110:111], 0
	v_mov_b64_e32 v[112:113], 0
	v_mov_b64_e32 v[114:115], 0
	v_mov_b64_e32 v[116:117], 0
	v_mov_b64_e32 v[118:119], 0
	v_mov_b64_e32 v[120:121], 0
	v_mov_b64_e32 v[122:123], 0
	v_mov_b64_e32 v[124:125], 0
	v_mov_b64_e32 v[126:127], 0

; #define PG8_WAIT_V(n) asm volatile("s_waitcnt vmcnt(" #n ")" ::: "memory")
;     ...
;         const bool has_next = S.next(ui + 1, nxt);
;         const char* nA = has_next ? (const char*)g.A + (size_t)nxt.pm * tA : cA; const char* nB = has_next ? (const char*)g.Bt + (size_t)nxt.pn * tB : cB;
; #pragma unroll 1
;         for (int t = 0; t < nt; t += 2) {
;             const bool last = (t == nt - 2);
;             const char* a1 = cA + (size_t)(t + 1) * kstep;
;             const char* a2 = last ? nA : cA + (size_t)(t + 2) * kstep; const char* b2 = last ? nB : cB + (size_t)(t + 2) * kstep;
;             const char* a3 = a2 + kstep; const char* b3 = b2 + kstep;
;             if (last && has_next) PG8_A_READY(nxt);
;             PG8_LDB(B0, 0, 0); PG8_SCHED; PG8_LDA(At, 0, 0); PG8_STAGE(PG8_SA(1, 1), a1 + hA, voffA);
;             PG8_WAIT_L(8); PG8_BAR; PG8_WAIT_L(0); PG8_MMA(0, 0, At, B0); PG8_BAR; PG8_SCHED;
;             PG8_LDB(B1, 0, 1); PG8_STAGE(PG8_SB(0, 0), b2, voffB);
;             PG8_BAR; PG8_WAIT_L(0); PG8_MMA(0, 1, At, B1); PG8_BAR;
;             PG8_LDA(At, 0, 1); PG8_STAGE(PG8_SA(0, 0), a2, voffA);
;             PG8_BAR; PG8_WAIT_L(0); PG8_MMA(1, 0, At, B0); PG8_BAR; PG8_SCHED;
;             PG8_STAGE(PG8_SB(0, 1), b2 + hB, voffB);
;             PG8_WAIT_V(6); PG8_BAR; PG8_MMA(1, 1, At, B1); PG8_BAR;
;             PG8_LDB(B0, 1, 0); PG8_SCHED; PG8_LDA(At, 1, 0); PG8_STAGE(PG8_SA(0, 1), a2 + hA, voffA);
;             PG8_WAIT_L(8); PG8_BAR; PG8_WAIT_L(0); PG8_MMA(0, 0, At, B0); PG8_BAR; PG8_SCHED;
;             PG8_LDB(B1, 1, 1); PG8_STAGE(PG8_SB(1, 0), b3, voffB);
;             PG8_BAR; PG8_WAIT_L(0); PG8_MMA(0, 1, At, B1); PG8_BAR;
;             PG8_LDA(At, 1, 1); PG8_STAGE(PG8_SA(1, 0), a3, voffA);
;             PG8_BAR; PG8_WAIT_L(0); PG8_MMA(1, 0, At, B0); PG8_BAR; PG8_SCHED;
;             PG8_STAGE(PG8_SB(1, 1), b3 + hB, voffB);
;             PG8_WAIT_V(6); PG8_BAR; PG8_MMA(1, 1, At, B1); PG8_BAR;
;         }
;         E(acc, cur, wr, wc, fr, fq);
;         if (!has_next) break;
; #pragma unroll
;         for (int a = 0; a < 2; ++a)
; #pragma unroll
;             for (int b = 0; b < 2; ++b)
; #pragma unroll
;                 for (int m = 0; m < 4; ++m)
; #pragma unroll
;                     for (int n = 0; n < 2; ++n) acc[a][b][m][n] = (f32x4){0.f, 0.f, 0.f, 0.f};
;         cur = nxt; cA = nA; cB = nB; ++ui;
.LBB0_2160:
	s_ashr_i32 s35, s34, 31
	s_lshl_b64 s[36:37], s[34:35], 21
	s_add_u32 s36, s14, s36
	s_addc_u32 s37, s15, s37
	s_and_b64 s[38:39], s[12:13], exec
	s_cselect_b32 s33, s37, s53
	s_cselect_b32 s35, s36, s52
	s_ashr_i32 s31, s30, 31
	s_lshl_b64 s[38:39], s[30:31], 21
	s_add_u32 s38, s20, s38
	s_addc_u32 s39, s21, s39
	s_and_b64 s[44:45], s[12:13], exec
	s_cselect_b32 s31, s39, s55
	s_cselect_b32 s41, s38, s54
	s_add_u32 s43, s52, 0x100000
	s_addc_u32 s44, s53, 0
	s_lshl_b32 s56, s34, 6
	s_ashr_i32 s57, s56, 31
	s_lshl_b64 s[56:57], s[56:57], 2
	s_add_u32 s56, s66, s56
	v_mov_b32_e32 v0, 0
	s_addc_u32 s57, s67, s57
	s_mov_b32 s45, 0
	s_waitcnt lgkmcnt(0)
	v_mov_b32_e32 v1, v0
	v_mov_b64_e32 v[2:3], 0
	v_mov_b64_e32 v[4:5], 0
	v_mov_b64_e32 v[6:7], 0
	v_mov_b64_e32 v[8:9], 0
	v_mov_b64_e32 v[10:11], 0
	v_mov_b64_e32 v[12:13], 0
	v_mov_b64_e32 v[14:15], 0
	v_mov_b64_e32 v[16:17], 0
	v_mov_b64_e32 v[18:19], 0
	v_mov_b64_e32 v[20:21], 0
	v_mov_b64_e32 v[22:23], 0
	v_mov_b64_e32 v[24:25], 0
	v_mov_b64_e32 v[26:27], 0
	v_mov_b64_e32 v[28:29], 0
	v_mov_b64_e32 v[30:31], 0
	v_mov_b64_e32 v[32:33], 0
	v_mov_b64_e32 v[34:35], 0
	v_mov_b64_e32 v[36:37], 0
	v_mov_b64_e32 v[38:39], 0
	v_mov_b64_e32 v[40:41], 0
	v_mov_b64_e32 v[42:43], 0
	v_mov_b64_e32 v[44:45], 0
	v_mov_b64_e32 v[46:47], 0
	v_mov_b64_e32 v[48:49], 0
	v_mov_b64_e32 v[50:51], 0
	v_mov_b64_e32 v[52:53], 0
	v_mov_b64_e32 v[54:55], 0
	v_mov_b64_e32 v[56:57], 0
	v_mov_b64_e32 v[58:59], 0
	v_mov_b64_e32 v[60:61], 0
	v_mov_b64_e32 v[62:63], 0
	v_mov_b64_e32 v[64:65], 0
	v_mov_b64_e32 v[66:67], 0
	v_mov_b64_e32 v[68:69], 0
	v_mov_b64_e32 v[70:71], 0
	v_mov_b64_e32 v[72:73], 0
	v_mov_b64_e32 v[74:75], 0
	v_mov_b64_e32 v[76:77], 0
	v_mov_b64_e32 v[78:79], 0
	v_mov_b64_e32 v[80:81], 0
	v_mov_b64_e32 v[82:83], 0
	v_mov_b64_e32 v[84:85], 0
	v_mov_b64_e32 v[86:87], 0
	v_mov_b64_e32 v[88:89], 0
	v_mov_b64_e32 v[90:91], 0
	v_mov_b64_e32 v[92:93], 0
	v_mov_b64_e32 v[94:95], 0
	v_mov_b64_e32 v[96:97], 0
	v_mov_b64_e32 v[98:99], 0
	v_mov_b64_e32 v[100:101], 0
	v_mov_b64_e32 v[102:103], 0
	v_mov_b64_e32 v[104:105], 0
	v_mov_b64_e32 v[106:107], 0
	v_mov_b64_e32 v[108:109], 0
	v_mov_b64_e32 v[110:111], 0
	v_mov_b64_e32 v[112:113], 0
	v_mov_b64_e32 v[114:115], 0
	v_mov_b64_e32 v[116:117], 0
	v_mov_b64_e32 v[118:119], 0
	v_mov_b64_e32 v[120:121], 0
	v_mov_b64_e32 v[122:123], 0
	v_mov_b64_e32 v[124:125], 0
	v_mov_b64_e32 v[126:127], 0
	s_branch .LBB0_2164

; #define PG8_WAIT_V(n) asm volatile("s_waitcnt vmcnt(" #n ")" ::: "memory")
;     ...
;         const bool has_next = S.next(ui + 1, nxt);
;         const char* nA = has_next ? (const char*)g.A + (size_t)nxt.pm * tA : cA; const char* nB = has_next ? (const char*)g.Bt + (size_t)nxt.pn * tB : cB;
; #pragma unroll 1
;         for (int t = 0; t < nt; t += 2) {
;             const bool last = (t == nt - 2);
;             const char* a1 = cA + (size_t)(t + 1) * kstep;
;             const char* a2 = last ? nA : cA + (size_t)(t + 2) * kstep; const char* b2 = last ? nB : cB + (size_t)(t + 2) * kstep;
;             const char* a3 = a2 + kstep; const char* b3 = b2 + kstep;
;             if (last && has_next) PG8_A_READY(nxt);
;             PG8_LDB(B0, 0, 0); PG8_SCHED; PG8_LDA(At, 0, 0); PG8_STAGE(PG8_SA(1, 1), a1 + hA, voffA);
;             PG8_WAIT_L(8); PG8_BAR; PG8_WAIT_L(0); PG8_MMA(0, 0, At, B0); PG8_BAR; PG8_SCHED;
;             PG8_LDB(B1, 0, 1); PG8_STAGE(PG8_SB(0, 0), b2, voffB);
;             PG8_BAR; PG8_WAIT_L(0); PG8_MMA(0, 1, At, B1); PG8_BAR;
;             PG8_LDA(At, 0, 1); PG8_STAGE(PG8_SA(0, 0), a2, voffA);
;             PG8_BAR; PG8_WAIT_L(0); PG8_MMA(1, 0, At, B0); PG8_BAR; PG8_SCHED;
;             PG8_STAGE(PG8_SB(0, 1), b2 + hB, voffB);
;             PG8_WAIT_V(6); PG8_BAR; PG8_MMA(1, 1, At, B1); PG8_BAR;
;             PG8_LDB(B0, 1, 0); PG8_SCHED; PG8_LDA(At, 1, 0); PG8_STAGE(PG8_SA(0, 1), a2 + hA, voffA);
;             PG8_WAIT_L(8); PG8_BAR; PG8_WAIT_L(0); PG8_MMA(0, 0, At, B0); PG8_BAR; PG8_SCHED;
;             PG8_LDB(B1, 1, 1); PG8_STAGE(PG8_SB(1, 0), b3, voffB);
;             PG8_BAR; PG8_WAIT_L(0); PG8_MMA(0, 1, At, B1); PG8_BAR;
;             PG8_LDA(At, 1, 1); PG8_STAGE(PG8_SA(1, 0), a3, voffA);
;             PG8_BAR; PG8_WAIT_L(0); PG8_MMA(1, 0, At, B0); PG8_BAR; PG8_SCHED;
;             PG8_STAGE(PG8_SB(1, 1), b3 + hB, voffB);
;             PG8_WAIT_V(6); PG8_BAR; PG8_MMA(1, 1, At, B1); PG8_BAR;
;         }
;         E(acc, cur, wr, wc, fr, fq);
;         if (!has_next) break;
; #pragma unroll
;         for (int a = 0; a < 2; ++a)
; #pragma unroll
;             for (int b = 0; b < 2; ++b)
; #pragma unroll
;                 for (int m = 0; m < 4; ++m)
; #pragma unroll
;                     for (int n = 0; n < 2; ++n) acc[a][b][m][n] = (f32x4){0.f, 0.f, 0.f, 0.f};
;         cur = nxt; cA = nA; cB = nB; ++ui;
.LBB0_2229:
	s_ashr_i32 s43, s42, 31
	s_lshl_b64 s[54:55], s[42:43], 21
	s_add_u32 s54, s81, s54
	s_addc_u32 s55, s82, s55
	s_and_b64 s[56:57], s[52:53], exec
	s_cselect_b32 s43, s55, s31
	s_cselect_b32 s90, s54, s30
	s_ashr_i32 s41, s40, 31
	s_lshl_b64 s[56:57], s[40:41], 21
	s_add_u32 s56, s83, s56
	s_addc_u32 s57, s84, s57
	s_and_b64 s[58:59], s[52:53], exec
	s_cselect_b32 s41, s57, s35
	s_cselect_b32 s91, s56, s34
	s_add_u32 s92, s30, 0x100000
	s_addc_u32 s93, s31, 0
	s_lshl_b32 s58, s42, 6
	s_ashr_i32 s59, s58, 31
	s_lshl_b64 s[58:59], s[58:59], 2
	s_add_u32 s58, s68, s58
	v_mov_b32_e32 v0, 0
	s_addc_u32 s59, s69, s59
	s_mov_b32 s94, 0
	v_mov_b32_e32 v1, v0
	v_mov_b64_e32 v[2:3], 0
	v_mov_b64_e32 v[4:5], 0
	v_mov_b64_e32 v[6:7], 0
	v_mov_b64_e32 v[8:9], 0
	v_mov_b64_e32 v[10:11], 0
	v_mov_b64_e32 v[12:13], 0
	v_mov_b64_e32 v[14:15], 0
	v_mov_b64_e32 v[16:17], 0
	v_mov_b64_e32 v[18:19], 0
	v_mov_b64_e32 v[20:21], 0
	v_mov_b64_e32 v[22:23], 0
	v_mov_b64_e32 v[24:25], 0
	v_mov_b64_e32 v[26:27], 0
	v_mov_b64_e32 v[28:29], 0
	v_mov_b64_e32 v[30:31], 0
	v_mov_b64_e32 v[32:33], 0
	v_mov_b64_e32 v[34:35], 0
	v_mov_b64_e32 v[36:37], 0
	v_mov_b64_e32 v[38:39], 0
	v_mov_b64_e32 v[40:41], 0
	v_mov_b64_e32 v[42:43], 0
	v_mov_b64_e32 v[44:45], 0
	v_mov_b64_e32 v[46:47], 0
	v_mov_b64_e32 v[48:49], 0
	v_mov_b64_e32 v[50:51], 0
	v_mov_b64_e32 v[52:53], 0
	v_mov_b64_e32 v[54:55], 0
	v_mov_b64_e32 v[56:57], 0
	v_mov_b64_e32 v[58:59], 0
	v_mov_b64_e32 v[60:61], 0
	v_mov_b64_e32 v[62:63], 0
	v_mov_b64_e32 v[64:65], 0
	v_mov_b64_e32 v[66:67], 0
	v_mov_b64_e32 v[68:69], 0
	v_mov_b64_e32 v[70:71], 0
	v_mov_b64_e32 v[72:73], 0
	v_mov_b64_e32 v[74:75], 0
	v_mov_b64_e32 v[76:77], 0
	v_mov_b64_e32 v[78:79], 0
	v_mov_b64_e32 v[80:81], 0
	v_mov_b64_e32 v[82:83], 0
	v_mov_b64_e32 v[84:85], 0
	v_mov_b64_e32 v[86:87], 0
	v_mov_b64_e32 v[88:89], 0
	v_mov_b64_e32 v[90:91], 0
	v_mov_b64_e32 v[92:93], 0
	v_mov_b64_e32 v[94:95], 0
	v_mov_b64_e32 v[96:97], 0
	v_mov_b64_e32 v[98:99], 0
	v_mov_b64_e32 v[100:101], 0
	v_mov_b64_e32 v[102:103], 0
	v_mov_b64_e32 v[104:105], 0
	v_mov_b64_e32 v[106:107], 0
	v_mov_b64_e32 v[108:109], 0
	v_mov_b64_e32 v[110:111], 0
	v_mov_b64_e32 v[112:113], 0
	v_mov_b64_e32 v[114:115], 0
	v_mov_b64_e32 v[116:117], 0
	v_mov_b64_e32 v[118:119], 0
	v_mov_b64_e32 v[120:121], 0
	v_mov_b64_e32 v[122:123], 0
	v_mov_b64_e32 v[124:125], 0
	v_mov_b64_e32 v[126:127], 0
	s_branch .LBB0_2233
